# norm phase: four row buffers in flight with stamp-counted waits
# baseline (speedup 1.0000x reference)
; __device__ __forceinline__ void norm_phase(KP P, const float* g, const float* MODl, int shc, int scc, bool from_input, int npart) {
;     ...
;     const int lane = tid_ & 63, gw = bid_ * 8 + (tid_ >> 6), NGW = gridDim.x * 8;
;     float* H = (float*)(P->ws + WS_H); bf16_t* XN = (bf16_t*)(P->ws + WS_XN);
;     constexpr int RU = 3;
;     for (int row0 = gw; row0 < M; row0 += RU * NGW) {
;         float4 v[RU][4]; float ss[RU];
; #pragma unroll
;         for (int u = 0; u < RU; ++u) { const int row = row0 + u * NGW; ss[u] = 0.f;
;             if (row < M) { const int b = row / RPB, t = row - b * RPB;
;                 const float4* h = from_input ? (t < SEQ ? (const float4*)(P->x + ((size_t)b * SEQ + t) * DM) : (const float4*)(P->ctx + ((size_t)b * CTXL + (t - SEQ)) * DM)) : (const float4*)(H + (size_t)row * DM);
; #pragma unroll
;                 for (int j = 0; j < 4; ++j) { if (from_input) { const f32x4 t4 = __builtin_nontemporal_load((const f32x4*)h + lane + 64 * j); v[u][j] = make_float4(t4[0], t4[1], t4[2], t4[3]); }
;                     else v[u][j] = h[lane + 64 * j]; } } }
.LBB0_346:
	v_readfirstlane_b32 s0, v164
	s_load_dword s2, s[72:73], 0x0
	v_readlane_b32 s18, v254, 18
	v_readlane_b32 s19, v254, 19
	s_lshr_b32 s0, s0, 6
	s_lshl_b32 s6, s98, 3
	s_add_i32 s0, s0, s6
	s_cmp_eq_u32 s22, 3
	s_cselect_b32 s6, 56, 64
	s_mov_b32 s7, 0x6000
	s_cselect_b32 s7, 0x3000, s7
	s_cmp_eq_u32 s22, 0
	s_cselect_b32 s6, 48, s6
	s_cselect_b32 s7, 0, s7
	s_add_u32 s10, s18, s6
	s_addc_u32 s11, s19, 0
	s_load_dwordx2 s[10:11], s[10:11], 0x0
	v_readlane_b32 s8, v254, 26
	v_readlane_b32 s9, v254, 27
	v_readlane_b32 s60, v254, 20
	v_readlane_b32 s61, v254, 21
	v_readlane_b32 s31, v254, 28
	s_cmp_eq_u32 s70, 1
	s_cselect_b32 s3, 0, 10
	s_add_i32 s6, s70, -13
	s_cmp_lt_u32 s6, 12
	s_cselect_b32 s6, 0, 3
	s_cmp_eq_u32 s22, 8
	s_cselect_b32 s3, s6, s3
	s_add_u32 s8, s8, s7
	s_addc_u32 s9, s9, 0
	s_add_u32 s62, s60, 0x4200000
	s_addc_u32 s63, s61, 0
	s_load_dwordx2 s[20:21], s[18:19], 0x0
	s_load_dwordx2 s[18:19], s[18:19], 0x10
	s_lshl_b32 s31, s31, 12
	v_and_b32_e32 v120, 63, v164
	v_lshlrev_b32_e32 v112, 4, v120
	v_lshlrev_b32_e32 v113, 3, v120
	v_xor_b32_e32 v114, 1, v120
	v_lshlrev_b32_e32 v114, 2, v114
	v_xor_b32_e32 v115, 2, v120
	v_lshlrev_b32_e32 v115, 2, v115
	v_xor_b32_e32 v116, 4, v120
	v_lshlrev_b32_e32 v116, 2, v116
	v_xor_b32_e32 v117, 8, v120
	v_lshlrev_b32_e32 v117, 2, v117
	v_xor_b32_e32 v118, 16, v120
	v_lshlrev_b32_e32 v118, 2, v118
	v_xor_b32_e32 v119, 32, v120
	v_lshlrev_b32_e32 v119, 2, v119
	s_waitcnt lgkmcnt(0)
	s_lshl_b32 s2, s2, 3
	s_add_u32 s10, s10, s31
	s_addc_u32 s11, s11, 0
	global_load_dwordx4 v[64:67], v112, s[10:11] offset:0
	global_load_dwordx4 v[68:71], v112, s[10:11] offset:1024
	global_load_dwordx4 v[72:75], v112, s[10:11] offset:2048
	global_load_dwordx4 v[76:79], v112, s[10:11] offset:3072
	s_mov_b32 s22, -1
	s_mov_b32 s23, 4
	s_mov_b32 s12, 0
	s_mov_b32 s13, 0
	s_mov_b32 s14, 0
	s_mov_b32 s15, 0
	s_cmp_eq_u32 s70, 1
	s_cbranch_scc1 .Lnm_fi
	s_mov_b32 s31, s0
	s_lshl_b32 s6, s31, 12
	s_add_u32 s64, s60, s6
	s_addc_u32 s65, s61, 0
	global_load_dwordx4 v[0:3], v112, s[64:65] offset:0
	global_load_dwordx4 v[4:7], v112, s[64:65] offset:1024
	global_load_dwordx4 v[8:11], v112, s[64:65] offset:2048
	global_load_dwordx4 v[12:15], v112, s[64:65] offset:3072
	s_add_u32 s23, s23, 4
	s_mov_b32 s12, s23
	s_add_i32 s31, s31, s2
	s_cmp_lt_u32 s31, 0x4200
	s_cbranch_scc0 .Lnm_fh_prod
	s_lshl_b32 s6, s31, 12
	s_add_u32 s64, s60, s6
	s_addc_u32 s65, s61, 0
	global_load_dwordx4 v[16:19], v112, s[64:65] offset:0
	global_load_dwordx4 v[20:23], v112, s[64:65] offset:1024
	global_load_dwordx4 v[24:27], v112, s[64:65] offset:2048
	global_load_dwordx4 v[28:31], v112, s[64:65] offset:3072
	s_add_u32 s23, s23, 4
	s_mov_b32 s13, s23
	s_add_i32 s31, s31, s2
	s_cmp_lt_u32 s31, 0x4200
	s_cbranch_scc0 .Lnm_fh_prod
	s_lshl_b32 s6, s31, 12
	s_add_u32 s64, s60, s6
	s_addc_u32 s65, s61, 0
	global_load_dwordx4 v[32:35], v112, s[64:65] offset:0
	global_load_dwordx4 v[36:39], v112, s[64:65] offset:1024
	global_load_dwordx4 v[40:43], v112, s[64:65] offset:2048
	global_load_dwordx4 v[44:47], v112, s[64:65] offset:3072
	s_add_u32 s23, s23, 4
	s_mov_b32 s14, s23
	s_add_i32 s31, s31, s2
	s_cmp_lt_u32 s31, 0x4200
	s_cbranch_scc0 .Lnm_fh_prod
	s_lshl_b32 s6, s31, 12
	s_add_u32 s64, s60, s6
	s_addc_u32 s65, s61, 0
	global_load_dwordx4 v[48:51], v112, s[64:65] offset:0
	global_load_dwordx4 v[52:55], v112, s[64:65] offset:1024
	global_load_dwordx4 v[56:59], v112, s[64:65] offset:2048
	global_load_dwordx4 v[60:63], v112, s[64:65] offset:3072
	s_add_u32 s23, s23, 4
	s_mov_b32 s15, s23
.Lnm_fh_prod:
.Lnm_fh0:
	s_sub_u32 s6, s23, s12
	s_lshr_b32 s6, s6, 2
	s_cmp_ge_u32 s6, 11
	s_cbranch_scc1 .Lnm_fh0_w11
	s_cmp_ge_u32 s6, 10
	s_cbranch_scc1 .Lnm_fh0_w10
	s_cmp_ge_u32 s6, 9
	s_cbranch_scc1 .Lnm_fh0_w9
	s_cmp_ge_u32 s6, 8
	s_cbranch_scc1 .Lnm_fh0_w8
	s_cmp_ge_u32 s6, 7
	s_cbranch_scc1 .Lnm_fh0_w7
	s_cmp_ge_u32 s6, 6
	s_cbranch_scc1 .Lnm_fh0_w6
	s_cmp_ge_u32 s6, 5
	s_cbranch_scc1 .Lnm_fh0_w5
	s_cmp_ge_u32 s6, 4
	s_cbranch_scc1 .Lnm_fh0_w4
	s_cmp_ge_u32 s6, 3
	s_cbranch_scc1 .Lnm_fh0_w3
	s_cmp_ge_u32 s6, 2
	s_cbranch_scc1 .Lnm_fh0_w2
	s_cmp_ge_u32 s6, 1
	s_cbranch_scc1 .Lnm_fh0_w1
	s_waitcnt vmcnt(0)
	s_branch .Lnm_fh0_wdone
.Lnm_fh0_w11:
	s_waitcnt vmcnt(44)
	s_branch .Lnm_fh0_wdone
.Lnm_fh0_w10:
	s_waitcnt vmcnt(40)
	s_branch .Lnm_fh0_wdone
.Lnm_fh0_w9:
	s_waitcnt vmcnt(36)
	s_branch .Lnm_fh0_wdone
.Lnm_fh0_w8:
	s_waitcnt vmcnt(32)
	s_branch .Lnm_fh0_wdone
.Lnm_fh0_w7:
	s_waitcnt vmcnt(28)
	s_branch .Lnm_fh0_wdone

; __device__ __forceinline__ void norm_phase(KP P, const float* g, const float* MODl, int shc, int scc, bool from_input, int npart) {
;     ...
;             if (row < M) { const int b = row / RPB, t = row - b * RPB, w = t >= SEQ ? 2 : b;
;                 if (t >= SEQ && npart > 0) {
;                     const float4* pp = (const float4*)(P->ws + WS_PART) + (size_t)(b * CTXL + (t - SEQ)) * 256 + lane;
;                     for (int q = 0; q < npart; ++q) {
; #pragma unroll
;                         for (int j = 0; j < 4; ++j) { const float4 a = pp[(size_t)q * 512 * 256 + 64 * j]; v[u][j].x += a.x; v[u][j].y += a.y; v[u][j].z += a.z; v[u][j].w += a.w; } } }
; #pragma unroll
;                 for (int j = 0; j < 4; ++j) ss[u] += v[u][j].x * v[u][j].x + v[u][j].y * v[u][j].y + v[u][j].z * v[u][j].z + v[u][j].w * v[u][j].w;
;                 if (from_input || (t >= SEQ && npart > 0)) {
; #pragma unroll
;                     for (int j = 0; j < 4; ++j) ((float4*)(H + (size_t)row * DM))[lane + 64 * j] = v[u][j]; }
.Lnm_fh0_w1:
	s_waitcnt vmcnt(4)
	s_branch .Lnm_fh0_wdone
.Lnm_fh0_wdone:
	s_cmp_ge_u32 s0, 0x2100
	s_cselect_b32 s6, 1, 0
	s_mul_i32 s7, s6, 0x2100
	s_sub_u32 s7, s0, s7
	s_cmp_ge_u32 s7, 0x2000
	s_cselect_b32 s30, 2, s6
	s_lshl_b32 s31, s0, 12
	s_add_u32 s64, s60, s31
	s_addc_u32 s65, s61, 0
	s_cmp_lt_u32 s7, 0x2000
	s_cbranch_scc1 .Lnm_fh0_nopart
	s_cmp_eq_u32 s3, 0
	s_cbranch_scc1 .Lnm_fh0_nopart
	s_lshl_b32 s6, s6, 8
	s_add_u32 s6, s6, s7
	s_sub_u32 s6, s6, 0x2000
	s_lshl_b32 s6, s6, 12
	s_add_u32 s10, s60, s6
	s_addc_u32 s11, s61, 0
	s_add_u32 s10, s10, 0x10e00000
	s_addc_u32 s11, s11, 0
	s_mov_b32 s31, s3
.Lnm_fh0_ploop:
	s_cmp_lt_u32 s31, 2
	s_cbranch_scc1 .Lnm_fh0_pone
	s_add_u32 s6, s10, 0x200000
	s_addc_u32 s7, s11, 0
	global_load_dwordx4 v[80:83], v112, s[10:11] offset:0
	global_load_dwordx4 v[84:87], v112, s[10:11] offset:1024
	global_load_dwordx4 v[88:91], v112, s[10:11] offset:2048
	global_load_dwordx4 v[92:95], v112, s[10:11] offset:3072
	global_load_dwordx4 v[96:99], v112, s[6:7] offset:0
	global_load_dwordx4 v[100:103], v112, s[6:7] offset:1024
	global_load_dwordx4 v[104:107], v112, s[6:7] offset:2048
	global_load_dwordx4 v[108:111], v112, s[6:7] offset:3072
	s_waitcnt vmcnt(0)
	v_pk_add_f32 v[0:1], v[0:1], v[80:81]
	v_pk_add_f32 v[2:3], v[2:3], v[82:83]
	v_pk_add_f32 v[4:5], v[4:5], v[84:85]
	v_pk_add_f32 v[6:7], v[6:7], v[86:87]
	v_pk_add_f32 v[8:9], v[8:9], v[88:89]
	v_pk_add_f32 v[10:11], v[10:11], v[90:91]
	v_pk_add_f32 v[12:13], v[12:13], v[92:93]
	v_pk_add_f32 v[14:15], v[14:15], v[94:95]
	v_pk_add_f32 v[0:1], v[0:1], v[96:97]
	v_pk_add_f32 v[2:3], v[2:3], v[98:99]
	v_pk_add_f32 v[4:5], v[4:5], v[100:101]
	v_pk_add_f32 v[6:7], v[6:7], v[102:103]
	v_pk_add_f32 v[8:9], v[8:9], v[104:105]
	v_pk_add_f32 v[10:11], v[10:11], v[106:107]
	v_pk_add_f32 v[12:13], v[12:13], v[108:109]
	v_pk_add_f32 v[14:15], v[14:15], v[110:111]
	s_add_u32 s10, s10, 0x400000
	s_addc_u32 s11, s11, 0
	s_sub_u32 s31, s31, 2
	s_branch .Lnm_fh0_ploop
.Lnm_fh0_pone:
	s_cmp_eq_u32 s31, 0
	s_cbranch_scc1 .Lnm_fh0_pdone
	global_load_dwordx4 v[80:83], v112, s[10:11] offset:0
	global_load_dwordx4 v[84:87], v112, s[10:11] offset:1024
	global_load_dwordx4 v[88:91], v112, s[10:11] offset:2048
	global_load_dwordx4 v[92:95], v112, s[10:11] offset:3072
	s_waitcnt vmcnt(0)
	v_pk_add_f32 v[0:1], v[0:1], v[80:81]
	v_pk_add_f32 v[2:3], v[2:3], v[82:83]
	v_pk_add_f32 v[4:5], v[4:5], v[84:85]
	v_pk_add_f32 v[6:7], v[6:7], v[86:87]
	v_pk_add_f32 v[8:9], v[8:9], v[88:89]
	v_pk_add_f32 v[10:11], v[10:11], v[90:91]
	v_pk_add_f32 v[12:13], v[12:13], v[92:93]
	v_pk_add_f32 v[14:15], v[14:15], v[94:95]
.Lnm_fh0_pdone:
	global_store_dwordx4 v112, v[0:3], s[64:65] offset:0
	global_store_dwordx4 v112, v[4:7], s[64:65] offset:1024
	global_store_dwordx4 v112, v[8:11], s[64:65] offset:2048
	global_store_dwordx4 v112, v[12:15], s[64:65] offset:3072
	s_add_u32 s23, s23, 4
	s_mov_b32 s22, -1
.Lnm_fh0_nopart:
	s_cmp_eq_u32 s30, s22
	s_cbranch_scc1 .Lnm_fh0_tabok
	s_mul_i32 s6, s30, 0x9000
	s_add_u32 s6, s8, s6
	s_addc_u32 s7, s9, 0
	global_load_dwordx4 v[80:83], v112, s[6:7] offset:0
	global_load_dwordx4 v[84:87], v112, s[6:7] offset:1024
	global_load_dwordx4 v[88:91], v112, s[6:7] offset:2048
	global_load_dwordx4 v[92:95], v112, s[6:7] offset:3072
	s_add_u32 s6, s6, 0x1000
	s_addc_u32 s7, s7, 0
	global_load_dwordx4 v[96:99], v112, s[6:7] offset:0
	global_load_dwordx4 v[100:103], v112, s[6:7] offset:1024
	global_load_dwordx4 v[104:107], v112, s[6:7] offset:2048
	global_load_dwordx4 v[108:111], v112, s[6:7] offset:3072
	s_waitcnt vmcnt(0)
	v_pk_add_f32 v[96:97], v[96:97], 1.0 op_sel_hi:[1,0]
	v_pk_add_f32 v[98:99], v[98:99], 1.0 op_sel_hi:[1,0]
	v_pk_add_f32 v[100:101], v[100:101], 1.0 op_sel_hi:[1,0]
	v_pk_add_f32 v[102:103], v[102:103], 1.0 op_sel_hi:[1,0]
	v_pk_add_f32 v[104:105], v[104:105], 1.0 op_sel_hi:[1,0]
	v_pk_add_f32 v[106:107], v[106:107], 1.0 op_sel_hi:[1,0]
	v_pk_add_f32 v[108:109], v[108:109], 1.0 op_sel_hi:[1,0]
	v_pk_add_f32 v[110:111], v[110:111], 1.0 op_sel_hi:[1,0]
	s_mov_b32 s22, s30
; __device__ __forceinline__ unsigned pk2(float lo, float hi) { return (unsigned)f2bf(lo) | ((unsigned)f2bf(hi) << 16); }
; __device__ __forceinline__ void norm_phase(KP P, const float* g, const float* MODl, int shc, int scc, bool from_input, int npart) {
;     ...
;                 for (int j = 0; j < 4; ++j) ss[u] += v[u][j].x * v[u][j].x + v[u][j].y * v[u][j].y + v[u][j].z * v[u][j].z + v[u][j].w * v[u][j].w;
;                 if (from_input || (t >= SEQ && npart > 0)) {
; #pragma unroll
;                     for (int j = 0; j < 4; ++j) ((float4*)(H + (size_t)row * DM))[lane + 64 * j] = v[u][j]; }
;                 const float r = rsqrtf(wave_sum(ss[u]) * (1.f / DM) + 1e-6f);
;                 const float* sh = MODl + w * NMOD + shc * 1024; const float* sc = MODl + w * NMOD + scc * 1024;
; #pragma unroll
;                 for (int j = 0; j < 4; ++j) { const int c = (lane + 64 * j) * 4; const float4 gg = *(const float4*)(g + c), s4 = *(const float4*)(sh + c), c4 = *(const float4*)(sc + c);
;                     uint2 o; o.x = pk2(v[u][j].x * r * gg.x * (1.f + c4.x) + s4.x, v[u][j].y * r * gg.y * (1.f + c4.y) + s4.y);
;                     o.y = pk2(v[u][j].z * r * gg.z * (1.f + c4.z) + s4.z, v[u][j].w * r * gg.w * (1.f + c4.w) + s4.w);
;                     *(uint2*)(XN + (size_t)row * DM + c) = o; } } }
.Lnm_fh0_tabok:
	v_pk_mul_f32 v[120:121], v[0:1], v[0:1]
	v_add_f32_e32 v125, v121, v120
	v_pk_mul_f32 v[120:121], v[2:3], v[2:3]
	v_add_f32_e32 v125, v120, v125
	v_add_f32_e32 v125, v121, v125
	v_pk_mul_f32 v[120:121], v[4:5], v[4:5]
	v_add_f32_e32 v124, v121, v120
	v_pk_mul_f32 v[120:121], v[6:7], v[6:7]
	v_add_f32_e32 v124, v120, v124
	v_add_f32_e32 v124, v121, v124
	v_add_f32_e32 v125, v124, v125
	v_pk_mul_f32 v[120:121], v[8:9], v[8:9]
	v_add_f32_e32 v124, v121, v120
	v_pk_mul_f32 v[120:121], v[10:11], v[10:11]
	v_add_f32_e32 v124, v120, v124
	v_add_f32_e32 v124, v121, v124
	v_add_f32_e32 v125, v124, v125
	v_pk_mul_f32 v[120:121], v[12:13], v[12:13]
	v_add_f32_e32 v124, v121, v120
	v_pk_mul_f32 v[120:121], v[14:15], v[14:15]
	v_add_f32_e32 v124, v120, v124
	v_add_f32_e32 v124, v121, v124
	v_add_f32_e32 v125, v124, v125
	ds_bpermute_b32 v120, v114, v125
	s_waitcnt lgkmcnt(0)
	v_add_f32_e32 v125, v125, v120
	ds_bpermute_b32 v120, v115, v125
	s_waitcnt lgkmcnt(0)
	v_add_f32_e32 v125, v125, v120
	ds_bpermute_b32 v120, v116, v125
	s_waitcnt lgkmcnt(0)
	v_add_f32_e32 v125, v125, v120
	ds_bpermute_b32 v120, v117, v125
	s_waitcnt lgkmcnt(0)
	v_add_f32_e32 v125, v125, v120
	ds_bpermute_b32 v120, v118, v125
	s_waitcnt lgkmcnt(0)
	v_add_f32_e32 v125, v125, v120
	ds_bpermute_b32 v120, v119, v125
	s_waitcnt lgkmcnt(0)
	v_add_f32_e32 v125, v125, v120
	v_fmamk_f32 v125, v125, 0x3a800000, v217
	v_rsq_f32_e32 v122, v125
	s_lshl_b32 s31, s0, 11
	s_add_u32 s6, s62, s31
	s_addc_u32 s7, s63, 0
	v_pk_mul_f32 v[124:125], v[0:1], v[122:123] op_sel_hi:[1,0]
	v_pk_mul_f32 v[124:125], v[64:65], v[124:125]
	v_pk_fma_f32 v[124:125], v[96:97], v[124:125], v[80:81]
	v_pk_mul_f32 v[120:121], v[2:3], v[122:123] op_sel_hi:[1,0]
	v_pk_mul_f32 v[120:121], v[66:67], v[120:121]
	v_pk_fma_f32 v[120:121], v[98:99], v[120:121], v[82:83]
	v_cvt_pk_bf16_f32 v124, v124, v125
	v_cvt_pk_bf16_f32 v125, v120, v121
	global_store_dwordx2 v113, v[124:125], s[6:7] offset:0
	v_pk_mul_f32 v[124:125], v[4:5], v[122:123] op_sel_hi:[1,0]
	v_pk_mul_f32 v[124:125], v[68:69], v[124:125]
	v_pk_fma_f32 v[124:125], v[100:101], v[124:125], v[84:85]
	v_pk_mul_f32 v[120:121], v[6:7], v[122:123] op_sel_hi:[1,0]
	v_pk_mul_f32 v[120:121], v[70:71], v[120:121]
	v_pk_fma_f32 v[120:121], v[102:103], v[120:121], v[86:87]
	v_cvt_pk_bf16_f32 v124, v124, v125
	v_cvt_pk_bf16_f32 v125, v120, v121
	global_store_dwordx2 v113, v[124:125], s[6:7] offset:512
	v_pk_mul_f32 v[124:125], v[8:9], v[122:123] op_sel_hi:[1,0]
	v_pk_mul_f32 v[124:125], v[72:73], v[124:125]
	v_pk_fma_f32 v[124:125], v[104:105], v[124:125], v[88:89]
	v_pk_mul_f32 v[120:121], v[10:11], v[122:123] op_sel_hi:[1,0]
	v_pk_mul_f32 v[120:121], v[74:75], v[120:121]
	v_pk_fma_f32 v[120:121], v[106:107], v[120:121], v[90:91]
	v_cvt_pk_bf16_f32 v124, v124, v125
	v_cvt_pk_bf16_f32 v125, v120, v121
	global_store_dwordx2 v113, v[124:125], s[6:7] offset:1024
	v_pk_mul_f32 v[124:125], v[12:13], v[122:123] op_sel_hi:[1,0]
	v_pk_mul_f32 v[124:125], v[76:77], v[124:125]
	v_pk_fma_f32 v[124:125], v[108:109], v[124:125], v[92:93]
	v_pk_mul_f32 v[120:121], v[14:15], v[122:123] op_sel_hi:[1,0]
	v_pk_mul_f32 v[120:121], v[78:79], v[120:121]
	v_pk_fma_f32 v[120:121], v[110:111], v[120:121], v[94:95]
	v_cvt_pk_bf16_f32 v124, v124, v125
	v_cvt_pk_bf16_f32 v125, v120, v121
	global_store_dwordx2 v113, v[124:125], s[6:7] offset:1536
	s_add_u32 s23, s23, 4
	s_mul_i32 s31, s2, 4
	s_add_i32 s31, s0, s31
	s_cmp_lt_u32 s31, 0x4200
	s_cbranch_scc0 .Lnm_fh0_nopf
	s_lshl_b32 s6, s31, 12
	s_add_u32 s64, s60, s6
	s_addc_u32 s65, s61, 0
	global_load_dwordx4 v[0:3], v112, s[64:65] offset:0
	global_load_dwordx4 v[4:7], v112, s[64:65] offset:1024
	global_load_dwordx4 v[8:11], v112, s[64:65] offset:2048
	global_load_dwordx4 v[12:15], v112, s[64:65] offset:3072
	s_add_u32 s23, s23, 4
	s_mov_b32 s12, s23

; __device__ __forceinline__ void norm_phase(KP P, const float* g, const float* MODl, int shc, int scc, bool from_input, int npart) {
;     ...
;     for (int row0 = gw; row0 < M; row0 += RU * NGW) {
;         float4 v[RU][4]; float ss[RU];
; #pragma unroll
;         for (int u = 0; u < RU; ++u) { const int row = row0 + u * NGW; ss[u] = 0.f;
;             if (row < M) { const int b = row / RPB, t = row - b * RPB;
;                 const float4* h = from_input ? (t < SEQ ? (const float4*)(P->x + ((size_t)b * SEQ + t) * DM) : (const float4*)(P->ctx + ((size_t)b * CTXL + (t - SEQ)) * DM)) : (const float4*)(H + (size_t)row * DM);
; #pragma unroll
;                 for (int j = 0; j < 4; ++j) { if (from_input) { const f32x4 t4 = __builtin_nontemporal_load((const f32x4*)h + lane + 64 * j); v[u][j] = make_float4(t4[0], t4[1], t4[2], t4[3]); }
;                     else v[u][j] = h[lane + 64 * j]; } } }
.Lnm_fh1:
	s_sub_u32 s6, s23, s13
	s_lshr_b32 s6, s6, 2
	s_cmp_ge_u32 s6, 11
	s_cbranch_scc1 .Lnm_fh1_w11
	s_cmp_ge_u32 s6, 10
	s_cbranch_scc1 .Lnm_fh1_w10
	s_cmp_ge_u32 s6, 9
	s_cbranch_scc1 .Lnm_fh1_w9
	s_cmp_ge_u32 s6, 8
	s_cbranch_scc1 .Lnm_fh1_w8
	s_cmp_ge_u32 s6, 7
	s_cbranch_scc1 .Lnm_fh1_w7
	s_cmp_ge_u32 s6, 6
	s_cbranch_scc1 .Lnm_fh1_w6
	s_cmp_ge_u32 s6, 5
	s_cbranch_scc1 .Lnm_fh1_w5
	s_cmp_ge_u32 s6, 4
	s_cbranch_scc1 .Lnm_fh1_w4
	s_cmp_ge_u32 s6, 3
	s_cbranch_scc1 .Lnm_fh1_w3
	s_cmp_ge_u32 s6, 2
	s_cbranch_scc1 .Lnm_fh1_w2
	s_cmp_ge_u32 s6, 1
	s_cbranch_scc1 .Lnm_fh1_w1
	s_waitcnt vmcnt(0)
	s_branch .Lnm_fh1_wdone

; __device__ __forceinline__ void norm_phase(KP P, const float* g, const float* MODl, int shc, int scc, bool from_input, int npart) {
;     ...
;             if (row < M) { const int b = row / RPB, t = row - b * RPB, w = t >= SEQ ? 2 : b;
;                 if (t >= SEQ && npart > 0) {
;                     const float4* pp = (const float4*)(P->ws + WS_PART) + (size_t)(b * CTXL + (t - SEQ)) * 256 + lane;
;                     for (int q = 0; q < npart; ++q) {
; #pragma unroll
;                         for (int j = 0; j < 4; ++j) { const float4 a = pp[(size_t)q * 512 * 256 + 64 * j]; v[u][j].x += a.x; v[u][j].y += a.y; v[u][j].z += a.z; v[u][j].w += a.w; } } }
; #pragma unroll
;                 for (int j = 0; j < 4; ++j) ss[u] += v[u][j].x * v[u][j].x + v[u][j].y * v[u][j].y + v[u][j].z * v[u][j].z + v[u][j].w * v[u][j].w;
;                 if (from_input || (t >= SEQ && npart > 0)) {
; #pragma unroll
;                     for (int j = 0; j < 4; ++j) ((float4*)(H + (size_t)row * DM))[lane + 64 * j] = v[u][j]; }
.Lnm_fh1_w1:
	s_waitcnt vmcnt(4)
	s_branch .Lnm_fh1_wdone
.Lnm_fh1_wdone:
	s_cmp_ge_u32 s0, 0x2100
	s_cselect_b32 s6, 1, 0
	s_mul_i32 s7, s6, 0x2100
	s_sub_u32 s7, s0, s7
	s_cmp_ge_u32 s7, 0x2000
	s_cselect_b32 s30, 2, s6
	s_lshl_b32 s31, s0, 12
	s_add_u32 s64, s60, s31
	s_addc_u32 s65, s61, 0
	s_cmp_lt_u32 s7, 0x2000
	s_cbranch_scc1 .Lnm_fh1_nopart
	s_cmp_eq_u32 s3, 0
	s_cbranch_scc1 .Lnm_fh1_nopart
	s_lshl_b32 s6, s6, 8
	s_add_u32 s6, s6, s7
	s_sub_u32 s6, s6, 0x2000
	s_lshl_b32 s6, s6, 12
	s_add_u32 s10, s60, s6
	s_addc_u32 s11, s61, 0
	s_add_u32 s10, s10, 0x10e00000
	s_addc_u32 s11, s11, 0
	s_mov_b32 s31, s3
.Lnm_fh1_ploop:
	s_cmp_lt_u32 s31, 2
	s_cbranch_scc1 .Lnm_fh1_pone
	s_add_u32 s6, s10, 0x200000
	s_addc_u32 s7, s11, 0
	global_load_dwordx4 v[80:83], v112, s[10:11] offset:0
	global_load_dwordx4 v[84:87], v112, s[10:11] offset:1024
	global_load_dwordx4 v[88:91], v112, s[10:11] offset:2048
	global_load_dwordx4 v[92:95], v112, s[10:11] offset:3072
	global_load_dwordx4 v[96:99], v112, s[6:7] offset:0
	global_load_dwordx4 v[100:103], v112, s[6:7] offset:1024
	global_load_dwordx4 v[104:107], v112, s[6:7] offset:2048
	global_load_dwordx4 v[108:111], v112, s[6:7] offset:3072
	s_waitcnt vmcnt(0)
	v_pk_add_f32 v[16:17], v[16:17], v[80:81]
	v_pk_add_f32 v[18:19], v[18:19], v[82:83]
	v_pk_add_f32 v[20:21], v[20:21], v[84:85]
	v_pk_add_f32 v[22:23], v[22:23], v[86:87]
	v_pk_add_f32 v[24:25], v[24:25], v[88:89]
	v_pk_add_f32 v[26:27], v[26:27], v[90:91]
	v_pk_add_f32 v[28:29], v[28:29], v[92:93]
	v_pk_add_f32 v[30:31], v[30:31], v[94:95]
	v_pk_add_f32 v[16:17], v[16:17], v[96:97]
	v_pk_add_f32 v[18:19], v[18:19], v[98:99]
	v_pk_add_f32 v[20:21], v[20:21], v[100:101]
	v_pk_add_f32 v[22:23], v[22:23], v[102:103]
	v_pk_add_f32 v[24:25], v[24:25], v[104:105]
	v_pk_add_f32 v[26:27], v[26:27], v[106:107]
	v_pk_add_f32 v[28:29], v[28:29], v[108:109]
	v_pk_add_f32 v[30:31], v[30:31], v[110:111]
	s_add_u32 s10, s10, 0x400000
	s_addc_u32 s11, s11, 0
	s_sub_u32 s31, s31, 2
	s_branch .Lnm_fh1_ploop
.Lnm_fh1_pone:
	s_cmp_eq_u32 s31, 0
	s_cbranch_scc1 .Lnm_fh1_pdone
	global_load_dwordx4 v[80:83], v112, s[10:11] offset:0
	global_load_dwordx4 v[84:87], v112, s[10:11] offset:1024
	global_load_dwordx4 v[88:91], v112, s[10:11] offset:2048
	global_load_dwordx4 v[92:95], v112, s[10:11] offset:3072
	s_waitcnt vmcnt(0)
	v_pk_add_f32 v[16:17], v[16:17], v[80:81]
	v_pk_add_f32 v[18:19], v[18:19], v[82:83]
	v_pk_add_f32 v[20:21], v[20:21], v[84:85]
	v_pk_add_f32 v[22:23], v[22:23], v[86:87]
	v_pk_add_f32 v[24:25], v[24:25], v[88:89]
	v_pk_add_f32 v[26:27], v[26:27], v[90:91]
	v_pk_add_f32 v[28:29], v[28:29], v[92:93]
	v_pk_add_f32 v[30:31], v[30:31], v[94:95]
.Lnm_fh1_pdone:
	global_store_dwordx4 v112, v[16:19], s[64:65] offset:0
	global_store_dwordx4 v112, v[20:23], s[64:65] offset:1024
	global_store_dwordx4 v112, v[24:27], s[64:65] offset:2048
	global_store_dwordx4 v112, v[28:31], s[64:65] offset:3072
	s_add_u32 s23, s23, 4
	s_mov_b32 s22, -1

; __device__ __forceinline__ unsigned pk2(float lo, float hi) { return (unsigned)f2bf(lo) | ((unsigned)f2bf(hi) << 16); }
; __device__ __forceinline__ void norm_phase(KP P, const float* g, const float* MODl, int shc, int scc, bool from_input, int npart) {
;     ...
;                 for (int j = 0; j < 4; ++j) ss[u] += v[u][j].x * v[u][j].x + v[u][j].y * v[u][j].y + v[u][j].z * v[u][j].z + v[u][j].w * v[u][j].w;
;                 if (from_input || (t >= SEQ && npart > 0)) {
; #pragma unroll
;                     for (int j = 0; j < 4; ++j) ((float4*)(H + (size_t)row * DM))[lane + 64 * j] = v[u][j]; }
;                 const float r = rsqrtf(wave_sum(ss[u]) * (1.f / DM) + 1e-6f);
;                 const float* sh = MODl + w * NMOD + shc * 1024; const float* sc = MODl + w * NMOD + scc * 1024;
; #pragma unroll
;                 for (int j = 0; j < 4; ++j) { const int c = (lane + 64 * j) * 4; const float4 gg = *(const float4*)(g + c), s4 = *(const float4*)(sh + c), c4 = *(const float4*)(sc + c);
;                     uint2 o; o.x = pk2(v[u][j].x * r * gg.x * (1.f + c4.x) + s4.x, v[u][j].y * r * gg.y * (1.f + c4.y) + s4.y);
;                     o.y = pk2(v[u][j].z * r * gg.z * (1.f + c4.z) + s4.z, v[u][j].w * r * gg.w * (1.f + c4.w) + s4.w);
;                     *(uint2*)(XN + (size_t)row * DM + c) = o; } } }
.Lnm_fh1_tabok:
	v_pk_mul_f32 v[120:121], v[16:17], v[16:17]
	v_add_f32_e32 v125, v121, v120
	v_pk_mul_f32 v[120:121], v[18:19], v[18:19]
	v_add_f32_e32 v125, v120, v125
	v_add_f32_e32 v125, v121, v125
	v_pk_mul_f32 v[120:121], v[20:21], v[20:21]
	v_add_f32_e32 v124, v121, v120
	v_pk_mul_f32 v[120:121], v[22:23], v[22:23]
	v_add_f32_e32 v124, v120, v124
	v_add_f32_e32 v124, v121, v124
	v_add_f32_e32 v125, v124, v125
	v_pk_mul_f32 v[120:121], v[24:25], v[24:25]
	v_add_f32_e32 v124, v121, v120
	v_pk_mul_f32 v[120:121], v[26:27], v[26:27]
	v_add_f32_e32 v124, v120, v124
	v_add_f32_e32 v124, v121, v124
	v_add_f32_e32 v125, v124, v125
	v_pk_mul_f32 v[120:121], v[28:29], v[28:29]
	v_add_f32_e32 v124, v121, v120
	v_pk_mul_f32 v[120:121], v[30:31], v[30:31]
	v_add_f32_e32 v124, v120, v124
	v_add_f32_e32 v124, v121, v124
	v_add_f32_e32 v125, v124, v125
	ds_bpermute_b32 v120, v114, v125
	s_waitcnt lgkmcnt(0)
	v_add_f32_e32 v125, v125, v120
	ds_bpermute_b32 v120, v115, v125
	s_waitcnt lgkmcnt(0)
	v_add_f32_e32 v125, v125, v120
	ds_bpermute_b32 v120, v116, v125
	s_waitcnt lgkmcnt(0)
	v_add_f32_e32 v125, v125, v120
	ds_bpermute_b32 v120, v117, v125
	s_waitcnt lgkmcnt(0)
	v_add_f32_e32 v125, v125, v120
	ds_bpermute_b32 v120, v118, v125
	s_waitcnt lgkmcnt(0)
	v_add_f32_e32 v125, v125, v120
	ds_bpermute_b32 v120, v119, v125
	s_waitcnt lgkmcnt(0)
	v_add_f32_e32 v125, v125, v120
	v_fmamk_f32 v125, v125, 0x3a800000, v217
	v_rsq_f32_e32 v122, v125
	s_lshl_b32 s31, s0, 11
	s_add_u32 s6, s62, s31
	s_addc_u32 s7, s63, 0
	v_pk_mul_f32 v[124:125], v[16:17], v[122:123] op_sel_hi:[1,0]
	v_pk_mul_f32 v[124:125], v[64:65], v[124:125]
	v_pk_fma_f32 v[124:125], v[96:97], v[124:125], v[80:81]
	v_pk_mul_f32 v[120:121], v[18:19], v[122:123] op_sel_hi:[1,0]
	v_pk_mul_f32 v[120:121], v[66:67], v[120:121]
	v_pk_fma_f32 v[120:121], v[98:99], v[120:121], v[82:83]
	v_cvt_pk_bf16_f32 v124, v124, v125
	v_cvt_pk_bf16_f32 v125, v120, v121
	global_store_dwordx2 v113, v[124:125], s[6:7] offset:0
	v_pk_mul_f32 v[124:125], v[20:21], v[122:123] op_sel_hi:[1,0]
	v_pk_mul_f32 v[124:125], v[68:69], v[124:125]
	v_pk_fma_f32 v[124:125], v[100:101], v[124:125], v[84:85]
	v_pk_mul_f32 v[120:121], v[22:23], v[122:123] op_sel_hi:[1,0]
	v_pk_mul_f32 v[120:121], v[70:71], v[120:121]
	v_pk_fma_f32 v[120:121], v[102:103], v[120:121], v[86:87]
	v_cvt_pk_bf16_f32 v124, v124, v125
	v_cvt_pk_bf16_f32 v125, v120, v121
	global_store_dwordx2 v113, v[124:125], s[6:7] offset:512
	v_pk_mul_f32 v[124:125], v[24:25], v[122:123] op_sel_hi:[1,0]
	v_pk_mul_f32 v[124:125], v[72:73], v[124:125]
	v_pk_fma_f32 v[124:125], v[104:105], v[124:125], v[88:89]
	v_pk_mul_f32 v[120:121], v[26:27], v[122:123] op_sel_hi:[1,0]
	v_pk_mul_f32 v[120:121], v[74:75], v[120:121]
	v_pk_fma_f32 v[120:121], v[106:107], v[120:121], v[90:91]
	v_cvt_pk_bf16_f32 v124, v124, v125
	v_cvt_pk_bf16_f32 v125, v120, v121
	global_store_dwordx2 v113, v[124:125], s[6:7] offset:1024
	v_pk_mul_f32 v[124:125], v[28:29], v[122:123] op_sel_hi:[1,0]
	v_pk_mul_f32 v[124:125], v[76:77], v[124:125]
	v_pk_fma_f32 v[124:125], v[108:109], v[124:125], v[92:93]
	v_pk_mul_f32 v[120:121], v[30:31], v[122:123] op_sel_hi:[1,0]
	v_pk_mul_f32 v[120:121], v[78:79], v[120:121]
	v_pk_fma_f32 v[120:121], v[110:111], v[120:121], v[94:95]
	v_cvt_pk_bf16_f32 v124, v124, v125
	v_cvt_pk_bf16_f32 v125, v120, v121
	global_store_dwordx2 v113, v[124:125], s[6:7] offset:1536
	s_add_u32 s23, s23, 4
	s_mul_i32 s31, s2, 4
	s_add_i32 s31, s0, s31
	s_cmp_lt_u32 s31, 0x4200
	s_cbranch_scc0 .Lnm_fh1_nopf
	s_lshl_b32 s6, s31, 12
	s_add_u32 s64, s60, s6
	s_addc_u32 s65, s61, 0
	global_load_dwordx4 v[16:19], v112, s[64:65] offset:0
	global_load_dwordx4 v[20:23], v112, s[64:65] offset:1024
	global_load_dwordx4 v[24:27], v112, s[64:65] offset:2048
	global_load_dwordx4 v[28:31], v112, s[64:65] offset:3072
	s_add_u32 s23, s23, 4
	s_mov_b32 s13, s23

; __device__ __forceinline__ void norm_phase(KP P, const float* g, const float* MODl, int shc, int scc, bool from_input, int npart) {
;     ...
;     for (int row0 = gw; row0 < M; row0 += RU * NGW) {
;         float4 v[RU][4]; float ss[RU];
; #pragma unroll
;         for (int u = 0; u < RU; ++u) { const int row = row0 + u * NGW; ss[u] = 0.f;
;             if (row < M) { const int b = row / RPB, t = row - b * RPB;
;                 const float4* h = from_input ? (t < SEQ ? (const float4*)(P->x + ((size_t)b * SEQ + t) * DM) : (const float4*)(P->ctx + ((size_t)b * CTXL + (t - SEQ)) * DM)) : (const float4*)(H + (size_t)row * DM);
; #pragma unroll
;                 for (int j = 0; j < 4; ++j) { if (from_input) { const f32x4 t4 = __builtin_nontemporal_load((const f32x4*)h + lane + 64 * j); v[u][j] = make_float4(t4[0], t4[1], t4[2], t4[3]); }
;                     else v[u][j] = h[lane + 64 * j]; } } }
.Lnm_fh2:
	s_sub_u32 s6, s23, s14
	s_lshr_b32 s6, s6, 2
	s_cmp_ge_u32 s6, 11
	s_cbranch_scc1 .Lnm_fh2_w11
	s_cmp_ge_u32 s6, 10
	s_cbranch_scc1 .Lnm_fh2_w10
	s_cmp_ge_u32 s6, 9
	s_cbranch_scc1 .Lnm_fh2_w9
	s_cmp_ge_u32 s6, 8
	s_cbranch_scc1 .Lnm_fh2_w8
	s_cmp_ge_u32 s6, 7
	s_cbranch_scc1 .Lnm_fh2_w7
	s_cmp_ge_u32 s6, 6
	s_cbranch_scc1 .Lnm_fh2_w6
	s_cmp_ge_u32 s6, 5
	s_cbranch_scc1 .Lnm_fh2_w5
	s_cmp_ge_u32 s6, 4
	s_cbranch_scc1 .Lnm_fh2_w4
	s_cmp_ge_u32 s6, 3
	s_cbranch_scc1 .Lnm_fh2_w3
	s_cmp_ge_u32 s6, 2
	s_cbranch_scc1 .Lnm_fh2_w2
	s_cmp_ge_u32 s6, 1
	s_cbranch_scc1 .Lnm_fh2_w1
	s_waitcnt vmcnt(0)
	s_branch .Lnm_fh2_wdone

; __device__ __forceinline__ void norm_phase(KP P, const float* g, const float* MODl, int shc, int scc, bool from_input, int npart) {
;     ...
;             if (row < M) { const int b = row / RPB, t = row - b * RPB, w = t >= SEQ ? 2 : b;
;                 if (t >= SEQ && npart > 0) {
;                     const float4* pp = (const float4*)(P->ws + WS_PART) + (size_t)(b * CTXL + (t - SEQ)) * 256 + lane;
;                     for (int q = 0; q < npart; ++q) {
; #pragma unroll
;                         for (int j = 0; j < 4; ++j) { const float4 a = pp[(size_t)q * 512 * 256 + 64 * j]; v[u][j].x += a.x; v[u][j].y += a.y; v[u][j].z += a.z; v[u][j].w += a.w; } } }
; #pragma unroll
;                 for (int j = 0; j < 4; ++j) ss[u] += v[u][j].x * v[u][j].x + v[u][j].y * v[u][j].y + v[u][j].z * v[u][j].z + v[u][j].w * v[u][j].w;
;                 if (from_input || (t >= SEQ && npart > 0)) {
; #pragma unroll
;                     for (int j = 0; j < 4; ++j) ((float4*)(H + (size_t)row * DM))[lane + 64 * j] = v[u][j]; }
.Lnm_fh2_w1:
	s_waitcnt vmcnt(4)
	s_branch .Lnm_fh2_wdone
.Lnm_fh2_wdone:
	s_cmp_ge_u32 s0, 0x2100
	s_cselect_b32 s6, 1, 0
	s_mul_i32 s7, s6, 0x2100
	s_sub_u32 s7, s0, s7
	s_cmp_ge_u32 s7, 0x2000
	s_cselect_b32 s30, 2, s6
	s_lshl_b32 s31, s0, 12
	s_add_u32 s64, s60, s31
	s_addc_u32 s65, s61, 0
	s_cmp_lt_u32 s7, 0x2000
	s_cbranch_scc1 .Lnm_fh2_nopart
	s_cmp_eq_u32 s3, 0
	s_cbranch_scc1 .Lnm_fh2_nopart
	s_lshl_b32 s6, s6, 8
	s_add_u32 s6, s6, s7
	s_sub_u32 s6, s6, 0x2000
	s_lshl_b32 s6, s6, 12
	s_add_u32 s10, s60, s6
	s_addc_u32 s11, s61, 0
	s_add_u32 s10, s10, 0x10e00000
	s_addc_u32 s11, s11, 0
	s_mov_b32 s31, s3
.Lnm_fh2_ploop:
	s_cmp_lt_u32 s31, 2
	s_cbranch_scc1 .Lnm_fh2_pone
	s_add_u32 s6, s10, 0x200000
	s_addc_u32 s7, s11, 0
	global_load_dwordx4 v[80:83], v112, s[10:11] offset:0
	global_load_dwordx4 v[84:87], v112, s[10:11] offset:1024
	global_load_dwordx4 v[88:91], v112, s[10:11] offset:2048
	global_load_dwordx4 v[92:95], v112, s[10:11] offset:3072
	global_load_dwordx4 v[96:99], v112, s[6:7] offset:0
	global_load_dwordx4 v[100:103], v112, s[6:7] offset:1024
	global_load_dwordx4 v[104:107], v112, s[6:7] offset:2048
	global_load_dwordx4 v[108:111], v112, s[6:7] offset:3072
	s_waitcnt vmcnt(0)
	v_pk_add_f32 v[32:33], v[32:33], v[80:81]
	v_pk_add_f32 v[34:35], v[34:35], v[82:83]
	v_pk_add_f32 v[36:37], v[36:37], v[84:85]
	v_pk_add_f32 v[38:39], v[38:39], v[86:87]
	v_pk_add_f32 v[40:41], v[40:41], v[88:89]
	v_pk_add_f32 v[42:43], v[42:43], v[90:91]
	v_pk_add_f32 v[44:45], v[44:45], v[92:93]
	v_pk_add_f32 v[46:47], v[46:47], v[94:95]
	v_pk_add_f32 v[32:33], v[32:33], v[96:97]
	v_pk_add_f32 v[34:35], v[34:35], v[98:99]
	v_pk_add_f32 v[36:37], v[36:37], v[100:101]
	v_pk_add_f32 v[38:39], v[38:39], v[102:103]
	v_pk_add_f32 v[40:41], v[40:41], v[104:105]
	v_pk_add_f32 v[42:43], v[42:43], v[106:107]
	v_pk_add_f32 v[44:45], v[44:45], v[108:109]
	v_pk_add_f32 v[46:47], v[46:47], v[110:111]
	s_add_u32 s10, s10, 0x400000
	s_addc_u32 s11, s11, 0
	s_sub_u32 s31, s31, 2
	s_branch .Lnm_fh2_ploop
.Lnm_fh2_pone:
	s_cmp_eq_u32 s31, 0
	s_cbranch_scc1 .Lnm_fh2_pdone
	global_load_dwordx4 v[80:83], v112, s[10:11] offset:0
	global_load_dwordx4 v[84:87], v112, s[10:11] offset:1024
	global_load_dwordx4 v[88:91], v112, s[10:11] offset:2048
	global_load_dwordx4 v[92:95], v112, s[10:11] offset:3072
	s_waitcnt vmcnt(0)
	v_pk_add_f32 v[32:33], v[32:33], v[80:81]
	v_pk_add_f32 v[34:35], v[34:35], v[82:83]
	v_pk_add_f32 v[36:37], v[36:37], v[84:85]
	v_pk_add_f32 v[38:39], v[38:39], v[86:87]
	v_pk_add_f32 v[40:41], v[40:41], v[88:89]
	v_pk_add_f32 v[42:43], v[42:43], v[90:91]
	v_pk_add_f32 v[44:45], v[44:45], v[92:93]
	v_pk_add_f32 v[46:47], v[46:47], v[94:95]
.Lnm_fh2_pdone:
	global_store_dwordx4 v112, v[32:35], s[64:65] offset:0
	global_store_dwordx4 v112, v[36:39], s[64:65] offset:1024
	global_store_dwordx4 v112, v[40:43], s[64:65] offset:2048
	global_store_dwordx4 v112, v[44:47], s[64:65] offset:3072
	s_add_u32 s23, s23, 4
	s_mov_b32 s22, -1

; __device__ __forceinline__ unsigned pk2(float lo, float hi) { return (unsigned)f2bf(lo) | ((unsigned)f2bf(hi) << 16); }
; __device__ __forceinline__ void norm_phase(KP P, const float* g, const float* MODl, int shc, int scc, bool from_input, int npart) {
;     ...
;                 for (int j = 0; j < 4; ++j) ss[u] += v[u][j].x * v[u][j].x + v[u][j].y * v[u][j].y + v[u][j].z * v[u][j].z + v[u][j].w * v[u][j].w;
;                 if (from_input || (t >= SEQ && npart > 0)) {
; #pragma unroll
;                     for (int j = 0; j < 4; ++j) ((float4*)(H + (size_t)row * DM))[lane + 64 * j] = v[u][j]; }
;                 const float r = rsqrtf(wave_sum(ss[u]) * (1.f / DM) + 1e-6f);
;                 const float* sh = MODl + w * NMOD + shc * 1024; const float* sc = MODl + w * NMOD + scc * 1024;
; #pragma unroll
;                 for (int j = 0; j < 4; ++j) { const int c = (lane + 64 * j) * 4; const float4 gg = *(const float4*)(g + c), s4 = *(const float4*)(sh + c), c4 = *(const float4*)(sc + c);
;                     uint2 o; o.x = pk2(v[u][j].x * r * gg.x * (1.f + c4.x) + s4.x, v[u][j].y * r * gg.y * (1.f + c4.y) + s4.y);
;                     o.y = pk2(v[u][j].z * r * gg.z * (1.f + c4.z) + s4.z, v[u][j].w * r * gg.w * (1.f + c4.w) + s4.w);
;                     *(uint2*)(XN + (size_t)row * DM + c) = o; } } }
.Lnm_fh2_tabok:
	v_pk_mul_f32 v[120:121], v[32:33], v[32:33]
	v_add_f32_e32 v125, v121, v120
	v_pk_mul_f32 v[120:121], v[34:35], v[34:35]
	v_add_f32_e32 v125, v120, v125
	v_add_f32_e32 v125, v121, v125
	v_pk_mul_f32 v[120:121], v[36:37], v[36:37]
	v_add_f32_e32 v124, v121, v120
	v_pk_mul_f32 v[120:121], v[38:39], v[38:39]
	v_add_f32_e32 v124, v120, v124
	v_add_f32_e32 v124, v121, v124
	v_add_f32_e32 v125, v124, v125
	v_pk_mul_f32 v[120:121], v[40:41], v[40:41]
	v_add_f32_e32 v124, v121, v120
	v_pk_mul_f32 v[120:121], v[42:43], v[42:43]
	v_add_f32_e32 v124, v120, v124
	v_add_f32_e32 v124, v121, v124
	v_add_f32_e32 v125, v124, v125
	v_pk_mul_f32 v[120:121], v[44:45], v[44:45]
	v_add_f32_e32 v124, v121, v120
	v_pk_mul_f32 v[120:121], v[46:47], v[46:47]
	v_add_f32_e32 v124, v120, v124
	v_add_f32_e32 v124, v121, v124
	v_add_f32_e32 v125, v124, v125
	ds_bpermute_b32 v120, v114, v125
	s_waitcnt lgkmcnt(0)
	v_add_f32_e32 v125, v125, v120
	ds_bpermute_b32 v120, v115, v125
	s_waitcnt lgkmcnt(0)
	v_add_f32_e32 v125, v125, v120
	ds_bpermute_b32 v120, v116, v125
	s_waitcnt lgkmcnt(0)
	v_add_f32_e32 v125, v125, v120
	ds_bpermute_b32 v120, v117, v125
	s_waitcnt lgkmcnt(0)
	v_add_f32_e32 v125, v125, v120
	ds_bpermute_b32 v120, v118, v125
	s_waitcnt lgkmcnt(0)
	v_add_f32_e32 v125, v125, v120
	ds_bpermute_b32 v120, v119, v125
	s_waitcnt lgkmcnt(0)
	v_add_f32_e32 v125, v125, v120
	v_fmamk_f32 v125, v125, 0x3a800000, v217
	v_rsq_f32_e32 v122, v125
	s_lshl_b32 s31, s0, 11
	s_add_u32 s6, s62, s31
	s_addc_u32 s7, s63, 0
	v_pk_mul_f32 v[124:125], v[32:33], v[122:123] op_sel_hi:[1,0]
	v_pk_mul_f32 v[124:125], v[64:65], v[124:125]
	v_pk_fma_f32 v[124:125], v[96:97], v[124:125], v[80:81]
	v_pk_mul_f32 v[120:121], v[34:35], v[122:123] op_sel_hi:[1,0]
	v_pk_mul_f32 v[120:121], v[66:67], v[120:121]
	v_pk_fma_f32 v[120:121], v[98:99], v[120:121], v[82:83]
	v_cvt_pk_bf16_f32 v124, v124, v125
	v_cvt_pk_bf16_f32 v125, v120, v121
	global_store_dwordx2 v113, v[124:125], s[6:7] offset:0
	v_pk_mul_f32 v[124:125], v[36:37], v[122:123] op_sel_hi:[1,0]
	v_pk_mul_f32 v[124:125], v[68:69], v[124:125]
	v_pk_fma_f32 v[124:125], v[100:101], v[124:125], v[84:85]
	v_pk_mul_f32 v[120:121], v[38:39], v[122:123] op_sel_hi:[1,0]
	v_pk_mul_f32 v[120:121], v[70:71], v[120:121]
	v_pk_fma_f32 v[120:121], v[102:103], v[120:121], v[86:87]
	v_cvt_pk_bf16_f32 v124, v124, v125
	v_cvt_pk_bf16_f32 v125, v120, v121
	global_store_dwordx2 v113, v[124:125], s[6:7] offset:512
	v_pk_mul_f32 v[124:125], v[40:41], v[122:123] op_sel_hi:[1,0]
	v_pk_mul_f32 v[124:125], v[72:73], v[124:125]
	v_pk_fma_f32 v[124:125], v[104:105], v[124:125], v[88:89]
	v_pk_mul_f32 v[120:121], v[42:43], v[122:123] op_sel_hi:[1,0]
	v_pk_mul_f32 v[120:121], v[74:75], v[120:121]
	v_pk_fma_f32 v[120:121], v[106:107], v[120:121], v[90:91]
	v_cvt_pk_bf16_f32 v124, v124, v125
	v_cvt_pk_bf16_f32 v125, v120, v121
	global_store_dwordx2 v113, v[124:125], s[6:7] offset:1024
	v_pk_mul_f32 v[124:125], v[44:45], v[122:123] op_sel_hi:[1,0]
	v_pk_mul_f32 v[124:125], v[76:77], v[124:125]
	v_pk_fma_f32 v[124:125], v[108:109], v[124:125], v[92:93]
	v_pk_mul_f32 v[120:121], v[46:47], v[122:123] op_sel_hi:[1,0]
	v_pk_mul_f32 v[120:121], v[78:79], v[120:121]
	v_pk_fma_f32 v[120:121], v[110:111], v[120:121], v[94:95]
	v_cvt_pk_bf16_f32 v124, v124, v125
	v_cvt_pk_bf16_f32 v125, v120, v121
	global_store_dwordx2 v113, v[124:125], s[6:7] offset:1536
	s_add_u32 s23, s23, 4
	s_mul_i32 s31, s2, 4
	s_add_i32 s31, s0, s31
	s_cmp_lt_u32 s31, 0x4200
	s_cbranch_scc0 .Lnm_fh2_nopf
	s_lshl_b32 s6, s31, 12
	s_add_u32 s64, s60, s6
	s_addc_u32 s65, s61, 0
	global_load_dwordx4 v[32:35], v112, s[64:65] offset:0
	global_load_dwordx4 v[36:39], v112, s[64:65] offset:1024
	global_load_dwordx4 v[40:43], v112, s[64:65] offset:2048
	global_load_dwordx4 v[44:47], v112, s[64:65] offset:3072
	s_add_u32 s23, s23, 4
	s_mov_b32 s14, s23

; __device__ __forceinline__ void norm_phase(KP P, const float* g, const float* MODl, int shc, int scc, bool from_input, int npart) {
;     ...
;     for (int row0 = gw; row0 < M; row0 += RU * NGW) {
;         float4 v[RU][4]; float ss[RU];
; #pragma unroll
;         for (int u = 0; u < RU; ++u) { const int row = row0 + u * NGW; ss[u] = 0.f;
;             if (row < M) { const int b = row / RPB, t = row - b * RPB;
;                 const float4* h = from_input ? (t < SEQ ? (const float4*)(P->x + ((size_t)b * SEQ + t) * DM) : (const float4*)(P->ctx + ((size_t)b * CTXL + (t - SEQ)) * DM)) : (const float4*)(H + (size_t)row * DM);
; #pragma unroll
;                 for (int j = 0; j < 4; ++j) { if (from_input) { const f32x4 t4 = __builtin_nontemporal_load((const f32x4*)h + lane + 64 * j); v[u][j] = make_float4(t4[0], t4[1], t4[2], t4[3]); }
;                     else v[u][j] = h[lane + 64 * j]; } } }
.Lnm_fh3:
	s_sub_u32 s6, s23, s15
	s_lshr_b32 s6, s6, 2
	s_cmp_ge_u32 s6, 11
	s_cbranch_scc1 .Lnm_fh3_w11
	s_cmp_ge_u32 s6, 10
	s_cbranch_scc1 .Lnm_fh3_w10
	s_cmp_ge_u32 s6, 9
	s_cbranch_scc1 .Lnm_fh3_w9
	s_cmp_ge_u32 s6, 8
	s_cbranch_scc1 .Lnm_fh3_w8
	s_cmp_ge_u32 s6, 7
	s_cbranch_scc1 .Lnm_fh3_w7
	s_cmp_ge_u32 s6, 6
	s_cbranch_scc1 .Lnm_fh3_w6
	s_cmp_ge_u32 s6, 5
	s_cbranch_scc1 .Lnm_fh3_w5
	s_cmp_ge_u32 s6, 4
	s_cbranch_scc1 .Lnm_fh3_w4
	s_cmp_ge_u32 s6, 3
	s_cbranch_scc1 .Lnm_fh3_w3
	s_cmp_ge_u32 s6, 2
	s_cbranch_scc1 .Lnm_fh3_w2
	s_cmp_ge_u32 s6, 1
	s_cbranch_scc1 .Lnm_fh3_w1
	s_waitcnt vmcnt(0)
	s_branch .Lnm_fh3_wdone

; __device__ __forceinline__ void norm_phase(KP P, const float* g, const float* MODl, int shc, int scc, bool from_input, int npart) {
;     ...
;             if (row < M) { const int b = row / RPB, t = row - b * RPB, w = t >= SEQ ? 2 : b;
;                 if (t >= SEQ && npart > 0) {
;                     const float4* pp = (const float4*)(P->ws + WS_PART) + (size_t)(b * CTXL + (t - SEQ)) * 256 + lane;
;                     for (int q = 0; q < npart; ++q) {
; #pragma unroll
;                         for (int j = 0; j < 4; ++j) { const float4 a = pp[(size_t)q * 512 * 256 + 64 * j]; v[u][j].x += a.x; v[u][j].y += a.y; v[u][j].z += a.z; v[u][j].w += a.w; } } }
; #pragma unroll
;                 for (int j = 0; j < 4; ++j) ss[u] += v[u][j].x * v[u][j].x + v[u][j].y * v[u][j].y + v[u][j].z * v[u][j].z + v[u][j].w * v[u][j].w;
;                 if (from_input || (t >= SEQ && npart > 0)) {
; #pragma unroll
;                     for (int j = 0; j < 4; ++j) ((float4*)(H + (size_t)row * DM))[lane + 64 * j] = v[u][j]; }
.Lnm_fh3_w1:
	s_waitcnt vmcnt(4)
	s_branch .Lnm_fh3_wdone
.Lnm_fh3_wdone:
	s_cmp_ge_u32 s0, 0x2100
	s_cselect_b32 s6, 1, 0
	s_mul_i32 s7, s6, 0x2100
	s_sub_u32 s7, s0, s7
	s_cmp_ge_u32 s7, 0x2000
	s_cselect_b32 s30, 2, s6
	s_lshl_b32 s31, s0, 12
	s_add_u32 s64, s60, s31
	s_addc_u32 s65, s61, 0
	s_cmp_lt_u32 s7, 0x2000
	s_cbranch_scc1 .Lnm_fh3_nopart
	s_cmp_eq_u32 s3, 0
	s_cbranch_scc1 .Lnm_fh3_nopart
	s_lshl_b32 s6, s6, 8
	s_add_u32 s6, s6, s7
	s_sub_u32 s6, s6, 0x2000
	s_lshl_b32 s6, s6, 12
	s_add_u32 s10, s60, s6
	s_addc_u32 s11, s61, 0
	s_add_u32 s10, s10, 0x10e00000
	s_addc_u32 s11, s11, 0
	s_mov_b32 s31, s3
.Lnm_fh3_ploop:
	s_cmp_lt_u32 s31, 2
	s_cbranch_scc1 .Lnm_fh3_pone
	s_add_u32 s6, s10, 0x200000
	s_addc_u32 s7, s11, 0
	global_load_dwordx4 v[80:83], v112, s[10:11] offset:0
	global_load_dwordx4 v[84:87], v112, s[10:11] offset:1024
	global_load_dwordx4 v[88:91], v112, s[10:11] offset:2048
	global_load_dwordx4 v[92:95], v112, s[10:11] offset:3072
	global_load_dwordx4 v[96:99], v112, s[6:7] offset:0
	global_load_dwordx4 v[100:103], v112, s[6:7] offset:1024
	global_load_dwordx4 v[104:107], v112, s[6:7] offset:2048
	global_load_dwordx4 v[108:111], v112, s[6:7] offset:3072
	s_waitcnt vmcnt(0)
	v_pk_add_f32 v[48:49], v[48:49], v[80:81]
	v_pk_add_f32 v[50:51], v[50:51], v[82:83]
	v_pk_add_f32 v[52:53], v[52:53], v[84:85]
	v_pk_add_f32 v[54:55], v[54:55], v[86:87]
	v_pk_add_f32 v[56:57], v[56:57], v[88:89]
	v_pk_add_f32 v[58:59], v[58:59], v[90:91]
	v_pk_add_f32 v[60:61], v[60:61], v[92:93]
	v_pk_add_f32 v[62:63], v[62:63], v[94:95]
	v_pk_add_f32 v[48:49], v[48:49], v[96:97]
	v_pk_add_f32 v[50:51], v[50:51], v[98:99]
	v_pk_add_f32 v[52:53], v[52:53], v[100:101]
	v_pk_add_f32 v[54:55], v[54:55], v[102:103]
	v_pk_add_f32 v[56:57], v[56:57], v[104:105]
	v_pk_add_f32 v[58:59], v[58:59], v[106:107]
	v_pk_add_f32 v[60:61], v[60:61], v[108:109]
	v_pk_add_f32 v[62:63], v[62:63], v[110:111]
	s_add_u32 s10, s10, 0x400000
	s_addc_u32 s11, s11, 0
	s_sub_u32 s31, s31, 2
	s_branch .Lnm_fh3_ploop
.Lnm_fh3_pone:
	s_cmp_eq_u32 s31, 0
	s_cbranch_scc1 .Lnm_fh3_pdone
	global_load_dwordx4 v[80:83], v112, s[10:11] offset:0
	global_load_dwordx4 v[84:87], v112, s[10:11] offset:1024
	global_load_dwordx4 v[88:91], v112, s[10:11] offset:2048
	global_load_dwordx4 v[92:95], v112, s[10:11] offset:3072
	s_waitcnt vmcnt(0)
	v_pk_add_f32 v[48:49], v[48:49], v[80:81]
	v_pk_add_f32 v[50:51], v[50:51], v[82:83]
	v_pk_add_f32 v[52:53], v[52:53], v[84:85]
	v_pk_add_f32 v[54:55], v[54:55], v[86:87]
	v_pk_add_f32 v[56:57], v[56:57], v[88:89]
	v_pk_add_f32 v[58:59], v[58:59], v[90:91]
	v_pk_add_f32 v[60:61], v[60:61], v[92:93]
	v_pk_add_f32 v[62:63], v[62:63], v[94:95]
.Lnm_fh3_pdone:
	global_store_dwordx4 v112, v[48:51], s[64:65] offset:0
	global_store_dwordx4 v112, v[52:55], s[64:65] offset:1024
	global_store_dwordx4 v112, v[56:59], s[64:65] offset:2048
	global_store_dwordx4 v112, v[60:63], s[64:65] offset:3072
	s_add_u32 s23, s23, 4
	s_mov_b32 s22, -1

; __device__ __forceinline__ unsigned pk2(float lo, float hi) { return (unsigned)f2bf(lo) | ((unsigned)f2bf(hi) << 16); }
; __device__ __forceinline__ void norm_phase(KP P, const float* g, const float* MODl, int shc, int scc, bool from_input, int npart) {
;     ...
;                 for (int j = 0; j < 4; ++j) ss[u] += v[u][j].x * v[u][j].x + v[u][j].y * v[u][j].y + v[u][j].z * v[u][j].z + v[u][j].w * v[u][j].w;
;                 if (from_input || (t >= SEQ && npart > 0)) {
; #pragma unroll
;                     for (int j = 0; j < 4; ++j) ((float4*)(H + (size_t)row * DM))[lane + 64 * j] = v[u][j]; }
;                 const float r = rsqrtf(wave_sum(ss[u]) * (1.f / DM) + 1e-6f);
;                 const float* sh = MODl + w * NMOD + shc * 1024; const float* sc = MODl + w * NMOD + scc * 1024;
; #pragma unroll
;                 for (int j = 0; j < 4; ++j) { const int c = (lane + 64 * j) * 4; const float4 gg = *(const float4*)(g + c), s4 = *(const float4*)(sh + c), c4 = *(const float4*)(sc + c);
;                     uint2 o; o.x = pk2(v[u][j].x * r * gg.x * (1.f + c4.x) + s4.x, v[u][j].y * r * gg.y * (1.f + c4.y) + s4.y);
;                     o.y = pk2(v[u][j].z * r * gg.z * (1.f + c4.z) + s4.z, v[u][j].w * r * gg.w * (1.f + c4.w) + s4.w);
;                     *(uint2*)(XN + (size_t)row * DM + c) = o; } } }
.Lnm_fh3_tabok:
	v_pk_mul_f32 v[120:121], v[48:49], v[48:49]
	v_add_f32_e32 v125, v121, v120
	v_pk_mul_f32 v[120:121], v[50:51], v[50:51]
	v_add_f32_e32 v125, v120, v125
	v_add_f32_e32 v125, v121, v125
	v_pk_mul_f32 v[120:121], v[52:53], v[52:53]
	v_add_f32_e32 v124, v121, v120
	v_pk_mul_f32 v[120:121], v[54:55], v[54:55]
	v_add_f32_e32 v124, v120, v124
	v_add_f32_e32 v124, v121, v124
	v_add_f32_e32 v125, v124, v125
	v_pk_mul_f32 v[120:121], v[56:57], v[56:57]
	v_add_f32_e32 v124, v121, v120
	v_pk_mul_f32 v[120:121], v[58:59], v[58:59]
	v_add_f32_e32 v124, v120, v124
	v_add_f32_e32 v124, v121, v124
	v_add_f32_e32 v125, v124, v125
	v_pk_mul_f32 v[120:121], v[60:61], v[60:61]
	v_add_f32_e32 v124, v121, v120
	v_pk_mul_f32 v[120:121], v[62:63], v[62:63]
	v_add_f32_e32 v124, v120, v124
	v_add_f32_e32 v124, v121, v124
	v_add_f32_e32 v125, v124, v125
	ds_bpermute_b32 v120, v114, v125
	s_waitcnt lgkmcnt(0)
	v_add_f32_e32 v125, v125, v120
	ds_bpermute_b32 v120, v115, v125
	s_waitcnt lgkmcnt(0)
	v_add_f32_e32 v125, v125, v120
	ds_bpermute_b32 v120, v116, v125
	s_waitcnt lgkmcnt(0)
	v_add_f32_e32 v125, v125, v120
	ds_bpermute_b32 v120, v117, v125
	s_waitcnt lgkmcnt(0)
	v_add_f32_e32 v125, v125, v120
	ds_bpermute_b32 v120, v118, v125
	s_waitcnt lgkmcnt(0)
	v_add_f32_e32 v125, v125, v120
	ds_bpermute_b32 v120, v119, v125
	s_waitcnt lgkmcnt(0)
	v_add_f32_e32 v125, v125, v120
	v_fmamk_f32 v125, v125, 0x3a800000, v217
	v_rsq_f32_e32 v122, v125
	s_lshl_b32 s31, s0, 11
	s_add_u32 s6, s62, s31
	s_addc_u32 s7, s63, 0
	v_pk_mul_f32 v[124:125], v[48:49], v[122:123] op_sel_hi:[1,0]
	v_pk_mul_f32 v[124:125], v[64:65], v[124:125]
	v_pk_fma_f32 v[124:125], v[96:97], v[124:125], v[80:81]
	v_pk_mul_f32 v[120:121], v[50:51], v[122:123] op_sel_hi:[1,0]
	v_pk_mul_f32 v[120:121], v[66:67], v[120:121]
	v_pk_fma_f32 v[120:121], v[98:99], v[120:121], v[82:83]
	v_cvt_pk_bf16_f32 v124, v124, v125
	v_cvt_pk_bf16_f32 v125, v120, v121
	global_store_dwordx2 v113, v[124:125], s[6:7] offset:0
	v_pk_mul_f32 v[124:125], v[52:53], v[122:123] op_sel_hi:[1,0]
	v_pk_mul_f32 v[124:125], v[68:69], v[124:125]
	v_pk_fma_f32 v[124:125], v[100:101], v[124:125], v[84:85]
	v_pk_mul_f32 v[120:121], v[54:55], v[122:123] op_sel_hi:[1,0]
	v_pk_mul_f32 v[120:121], v[70:71], v[120:121]
	v_pk_fma_f32 v[120:121], v[102:103], v[120:121], v[86:87]
	v_cvt_pk_bf16_f32 v124, v124, v125
	v_cvt_pk_bf16_f32 v125, v120, v121
	global_store_dwordx2 v113, v[124:125], s[6:7] offset:512
	v_pk_mul_f32 v[124:125], v[56:57], v[122:123] op_sel_hi:[1,0]
	v_pk_mul_f32 v[124:125], v[72:73], v[124:125]
	v_pk_fma_f32 v[124:125], v[104:105], v[124:125], v[88:89]
	v_pk_mul_f32 v[120:121], v[58:59], v[122:123] op_sel_hi:[1,0]
	v_pk_mul_f32 v[120:121], v[74:75], v[120:121]
	v_pk_fma_f32 v[120:121], v[106:107], v[120:121], v[90:91]
	v_cvt_pk_bf16_f32 v124, v124, v125
	v_cvt_pk_bf16_f32 v125, v120, v121
	global_store_dwordx2 v113, v[124:125], s[6:7] offset:1024
	v_pk_mul_f32 v[124:125], v[60:61], v[122:123] op_sel_hi:[1,0]
	v_pk_mul_f32 v[124:125], v[76:77], v[124:125]
	v_pk_fma_f32 v[124:125], v[108:109], v[124:125], v[92:93]
	v_pk_mul_f32 v[120:121], v[62:63], v[122:123] op_sel_hi:[1,0]
	v_pk_mul_f32 v[120:121], v[78:79], v[120:121]
	v_pk_fma_f32 v[120:121], v[110:111], v[120:121], v[94:95]
	v_cvt_pk_bf16_f32 v124, v124, v125
	v_cvt_pk_bf16_f32 v125, v120, v121
	global_store_dwordx2 v113, v[124:125], s[6:7] offset:1536
	s_add_u32 s23, s23, 4
	s_mul_i32 s31, s2, 4
	s_add_i32 s31, s0, s31
	s_cmp_lt_u32 s31, 0x4200
	s_cbranch_scc0 .Lnm_fh3_nopf
	s_lshl_b32 s6, s31, 12
	s_add_u32 s64, s60, s6
	s_addc_u32 s65, s61, 0
	global_load_dwordx4 v[48:51], v112, s[64:65] offset:0
	global_load_dwordx4 v[52:55], v112, s[64:65] offset:1024
	global_load_dwordx4 v[56:59], v112, s[64:65] offset:2048
	global_load_dwordx4 v[60:63], v112, s[64:65] offset:3072
	s_add_u32 s23, s23, 4
	s_mov_b32 s15, s23

; __device__ __forceinline__ void norm_phase(KP P, const float* g, const float* MODl, int shc, int scc, bool from_input, int npart) {
;     ...
;         for (int u = 0; u < RU; ++u) { const int row = row0 + u * NGW; ss[u] = 0.f;
;             if (row < M) { const int b = row / RPB, t = row - b * RPB;
;                 const float4* h = from_input ? (t < SEQ ? (const float4*)(P->x + ((size_t)b * SEQ + t) * DM) : (const float4*)(P->ctx + ((size_t)b * CTXL + (t - SEQ)) * DM)) : (const float4*)(H + (size_t)row * DM);
; #pragma unroll
;                 for (int j = 0; j < 4; ++j) { if (from_input) { const f32x4 t4 = __builtin_nontemporal_load((const f32x4*)h + lane + 64 * j); v[u][j] = make_float4(t4[0], t4[1], t4[2], t4[3]); }
.Lnm_fi:
	s_mov_b32 s31, s0
	s_cmp_ge_u32 s31, 0x2100
	s_cselect_b32 s6, 1, 0
	s_mul_i32 s7, s6, 0x2100
	s_sub_u32 s7, s31, s7
	s_cmp_ge_u32 s7, 0x2000
	s_cbranch_scc1 .Lnm_fi0_ctxp
	s_lshl_b32 s6, s6, 13
	s_add_u32 s6, s6, s7
	s_lshl_b32 s6, s6, 12
	s_add_u32 s64, s20, s6
	s_addc_u32 s65, s21, 0
	s_branch .Lnm_fi0_ptrd

; __device__ __forceinline__ void norm_phase(KP P, const float* g, const float* MODl, int shc, int scc, bool from_input, int npart) {
;     ...
;         for (int u = 0; u < RU; ++u) { const int row = row0 + u * NGW; ss[u] = 0.f;
;             if (row < M) { const int b = row / RPB, t = row - b * RPB;
;                 const float4* h = from_input ? (t < SEQ ? (const float4*)(P->x + ((size_t)b * SEQ + t) * DM) : (const float4*)(P->ctx + ((size_t)b * CTXL + (t - SEQ)) * DM)) : (const float4*)(H + (size_t)row * DM);
; #pragma unroll
;                 for (int j = 0; j < 4; ++j) { if (from_input) { const f32x4 t4 = __builtin_nontemporal_load((const f32x4*)h + lane + 64 * j); v[u][j] = make_float4(t4[0], t4[1], t4[2], t4[3]); }
;                     else v[u][j] = h[lane + 64 * j]; } } }
.Lnm_fi0_ptrd:
	global_load_dwordx4 v[0:3], v112, s[64:65] offset:0 nt
	global_load_dwordx4 v[4:7], v112, s[64:65] offset:1024 nt
	global_load_dwordx4 v[8:11], v112, s[64:65] offset:2048 nt
	global_load_dwordx4 v[12:15], v112, s[64:65] offset:3072 nt
	s_add_u32 s23, s23, 4
	s_mov_b32 s12, s23
	s_add_i32 s31, s31, s2
	s_cmp_lt_u32 s31, 0x4200
	s_cbranch_scc0 .Lnm_fi_prod
	s_cmp_ge_u32 s31, 0x2100
	s_cselect_b32 s6, 1, 0
	s_mul_i32 s7, s6, 0x2100
	s_sub_u32 s7, s31, s7
	s_cmp_ge_u32 s7, 0x2000
	s_cbranch_scc1 .Lnm_fi1_ctxp
	s_lshl_b32 s6, s6, 13
	s_add_u32 s6, s6, s7
	s_lshl_b32 s6, s6, 12
	s_add_u32 s64, s20, s6
	s_addc_u32 s65, s21, 0
	s_branch .Lnm_fi1_ptrd

; __device__ __forceinline__ void norm_phase(KP P, const float* g, const float* MODl, int shc, int scc, bool from_input, int npart) {
;     ...
;         for (int u = 0; u < RU; ++u) { const int row = row0 + u * NGW; ss[u] = 0.f;
;             if (row < M) { const int b = row / RPB, t = row - b * RPB;
;                 const float4* h = from_input ? (t < SEQ ? (const float4*)(P->x + ((size_t)b * SEQ + t) * DM) : (const float4*)(P->ctx + ((size_t)b * CTXL + (t - SEQ)) * DM)) : (const float4*)(H + (size_t)row * DM);
; #pragma unroll
;                 for (int j = 0; j < 4; ++j) { if (from_input) { const f32x4 t4 = __builtin_nontemporal_load((const f32x4*)h + lane + 64 * j); v[u][j] = make_float4(t4[0], t4[1], t4[2], t4[3]); }
;                     else v[u][j] = h[lane + 64 * j]; } } }
.Lnm_fi1_ptrd:
	global_load_dwordx4 v[16:19], v112, s[64:65] offset:0 nt
	global_load_dwordx4 v[20:23], v112, s[64:65] offset:1024 nt
	global_load_dwordx4 v[24:27], v112, s[64:65] offset:2048 nt
	global_load_dwordx4 v[28:31], v112, s[64:65] offset:3072 nt
	s_add_u32 s23, s23, 4
	s_mov_b32 s13, s23
	s_add_i32 s31, s31, s2
	s_cmp_lt_u32 s31, 0x4200
	s_cbranch_scc0 .Lnm_fi_prod
	s_cmp_ge_u32 s31, 0x2100
	s_cselect_b32 s6, 1, 0
	s_mul_i32 s7, s6, 0x2100
	s_sub_u32 s7, s31, s7
	s_cmp_ge_u32 s7, 0x2000
	s_cbranch_scc1 .Lnm_fi2_ctxp
	s_lshl_b32 s6, s6, 13
	s_add_u32 s6, s6, s7
	s_lshl_b32 s6, s6, 12
	s_add_u32 s64, s20, s6
	s_addc_u32 s65, s21, 0
	s_branch .Lnm_fi2_ptrd

; __device__ __forceinline__ void norm_phase(KP P, const float* g, const float* MODl, int shc, int scc, bool from_input, int npart) {
;     ...
;         for (int u = 0; u < RU; ++u) { const int row = row0 + u * NGW; ss[u] = 0.f;
;             if (row < M) { const int b = row / RPB, t = row - b * RPB;
;                 const float4* h = from_input ? (t < SEQ ? (const float4*)(P->x + ((size_t)b * SEQ + t) * DM) : (const float4*)(P->ctx + ((size_t)b * CTXL + (t - SEQ)) * DM)) : (const float4*)(H + (size_t)row * DM);
; #pragma unroll
;                 for (int j = 0; j < 4; ++j) { if (from_input) { const f32x4 t4 = __builtin_nontemporal_load((const f32x4*)h + lane + 64 * j); v[u][j] = make_float4(t4[0], t4[1], t4[2], t4[3]); }
;                     else v[u][j] = h[lane + 64 * j]; } } }
.Lnm_fi2_ptrd:
	global_load_dwordx4 v[32:35], v112, s[64:65] offset:0 nt
	global_load_dwordx4 v[36:39], v112, s[64:65] offset:1024 nt
	global_load_dwordx4 v[40:43], v112, s[64:65] offset:2048 nt
	global_load_dwordx4 v[44:47], v112, s[64:65] offset:3072 nt
	s_add_u32 s23, s23, 4
	s_mov_b32 s14, s23
	s_add_i32 s31, s31, s2
	s_cmp_lt_u32 s31, 0x4200
	s_cbranch_scc0 .Lnm_fi_prod
	s_cmp_ge_u32 s31, 0x2100
	s_cselect_b32 s6, 1, 0
	s_mul_i32 s7, s6, 0x2100
	s_sub_u32 s7, s31, s7
	s_cmp_ge_u32 s7, 0x2000
	s_cbranch_scc1 .Lnm_fi3_ctxp
	s_lshl_b32 s6, s6, 13
	s_add_u32 s6, s6, s7
	s_lshl_b32 s6, s6, 12
	s_add_u32 s64, s20, s6
	s_addc_u32 s65, s21, 0
	s_branch .Lnm_fi3_ptrd

; __device__ __forceinline__ void norm_phase(KP P, const float* g, const float* MODl, int shc, int scc, bool from_input, int npart) {
;     ...
;         for (int u = 0; u < RU; ++u) { const int row = row0 + u * NGW; ss[u] = 0.f;
;             if (row < M) { const int b = row / RPB, t = row - b * RPB;
;                 const float4* h = from_input ? (t < SEQ ? (const float4*)(P->x + ((size_t)b * SEQ + t) * DM) : (const float4*)(P->ctx + ((size_t)b * CTXL + (t - SEQ)) * DM)) : (const float4*)(H + (size_t)row * DM);
; #pragma unroll
;                 for (int j = 0; j < 4; ++j) { if (from_input) { const f32x4 t4 = __builtin_nontemporal_load((const f32x4*)h + lane + 64 * j); v[u][j] = make_float4(t4[0], t4[1], t4[2], t4[3]); }
;                     else v[u][j] = h[lane + 64 * j]; } } }
.Lnm_fi3_ptrd:
	global_load_dwordx4 v[48:51], v112, s[64:65] offset:0 nt
	global_load_dwordx4 v[52:55], v112, s[64:65] offset:1024 nt
	global_load_dwordx4 v[56:59], v112, s[64:65] offset:2048 nt
	global_load_dwordx4 v[60:63], v112, s[64:65] offset:3072 nt
	s_add_u32 s23, s23, 4
	s_mov_b32 s15, s23

; __device__ __forceinline__ unsigned pk2(float lo, float hi) { return (unsigned)f2bf(lo) | ((unsigned)f2bf(hi) << 16); }
; __device__ __forceinline__ void norm_phase(KP P, const float* g, const float* MODl, int shc, int scc, bool from_input, int npart) {
;     ...
;             if (row < M) { const int b = row / RPB, t = row - b * RPB, w = t >= SEQ ? 2 : b;
;                 if (t >= SEQ && npart > 0) {
;                     const float4* pp = (const float4*)(P->ws + WS_PART) + (size_t)(b * CTXL + (t - SEQ)) * 256 + lane;
;                     for (int q = 0; q < npart; ++q) {
; #pragma unroll
;                         for (int j = 0; j < 4; ++j) { const float4 a = pp[(size_t)q * 512 * 256 + 64 * j]; v[u][j].x += a.x; v[u][j].y += a.y; v[u][j].z += a.z; v[u][j].w += a.w; } } }
; #pragma unroll
;                 for (int j = 0; j < 4; ++j) ss[u] += v[u][j].x * v[u][j].x + v[u][j].y * v[u][j].y + v[u][j].z * v[u][j].z + v[u][j].w * v[u][j].w;
;                 if (from_input || (t >= SEQ && npart > 0)) {
; #pragma unroll
;                     for (int j = 0; j < 4; ++j) ((float4*)(H + (size_t)row * DM))[lane + 64 * j] = v[u][j]; }
;                 const float r = rsqrtf(wave_sum(ss[u]) * (1.f / DM) + 1e-6f);
;                 const float* sh = MODl + w * NMOD + shc * 1024; const float* sc = MODl + w * NMOD + scc * 1024;
; #pragma unroll
;                 for (int j = 0; j < 4; ++j) { const int c = (lane + 64 * j) * 4; const float4 gg = *(const float4*)(g + c), s4 = *(const float4*)(sh + c), c4 = *(const float4*)(sc + c);
;                     uint2 o; o.x = pk2(v[u][j].x * r * gg.x * (1.f + c4.x) + s4.x, v[u][j].y * r * gg.y * (1.f + c4.y) + s4.y);
;                     o.y = pk2(v[u][j].z * r * gg.z * (1.f + c4.z) + s4.z, v[u][j].w * r * gg.w * (1.f + c4.w) + s4.w);
;                     *(uint2*)(XN + (size_t)row * DM + c) = o; } } }
.Lnm_fi0_wdone:
	s_cmp_ge_u32 s0, 0x2100
	s_cselect_b32 s6, 1, 0
	s_mul_i32 s7, s6, 0x2100
	s_sub_u32 s7, s0, s7
	s_cmp_ge_u32 s7, 0x2000
	s_cselect_b32 s30, 2, s6
	s_lshl_b32 s31, s0, 12
	s_add_u32 s64, s60, s31
	s_addc_u32 s65, s61, 0
	s_cmp_eq_u32 s30, s22
	s_cbranch_scc1 .Lnm_fi0_tabok
	s_mul_i32 s6, s30, 0x9000
	s_add_u32 s6, s8, s6
	s_addc_u32 s7, s9, 0
	global_load_dwordx4 v[80:83], v112, s[6:7] offset:0
	global_load_dwordx4 v[84:87], v112, s[6:7] offset:1024
	global_load_dwordx4 v[88:91], v112, s[6:7] offset:2048
	global_load_dwordx4 v[92:95], v112, s[6:7] offset:3072
	s_add_u32 s6, s6, 0x1000
	s_addc_u32 s7, s7, 0
	global_load_dwordx4 v[96:99], v112, s[6:7] offset:0
	global_load_dwordx4 v[100:103], v112, s[6:7] offset:1024
	global_load_dwordx4 v[104:107], v112, s[6:7] offset:2048
	global_load_dwordx4 v[108:111], v112, s[6:7] offset:3072
	s_waitcnt vmcnt(0)
	v_pk_add_f32 v[96:97], v[96:97], 1.0 op_sel_hi:[1,0]
	v_pk_add_f32 v[98:99], v[98:99], 1.0 op_sel_hi:[1,0]
	v_pk_add_f32 v[100:101], v[100:101], 1.0 op_sel_hi:[1,0]
	v_pk_add_f32 v[102:103], v[102:103], 1.0 op_sel_hi:[1,0]
	v_pk_add_f32 v[104:105], v[104:105], 1.0 op_sel_hi:[1,0]
	v_pk_add_f32 v[106:107], v[106:107], 1.0 op_sel_hi:[1,0]
	v_pk_add_f32 v[108:109], v[108:109], 1.0 op_sel_hi:[1,0]
	v_pk_add_f32 v[110:111], v[110:111], 1.0 op_sel_hi:[1,0]
	s_mov_b32 s22, s30
.Lnm_fi0_tabok:
	global_store_dwordx4 v112, v[0:3], s[64:65] offset:0
	global_store_dwordx4 v112, v[4:7], s[64:65] offset:1024
	global_store_dwordx4 v112, v[8:11], s[64:65] offset:2048
	global_store_dwordx4 v112, v[12:15], s[64:65] offset:3072
	s_add_u32 s23, s23, 4
	v_pk_mul_f32 v[120:121], v[0:1], v[0:1]
	v_add_f32_e32 v125, v121, v120
	v_pk_mul_f32 v[120:121], v[2:3], v[2:3]
	v_add_f32_e32 v125, v120, v125
	v_add_f32_e32 v125, v121, v125
	v_pk_mul_f32 v[120:121], v[4:5], v[4:5]
	v_add_f32_e32 v124, v121, v120
	v_pk_mul_f32 v[120:121], v[6:7], v[6:7]
	v_add_f32_e32 v124, v120, v124
	v_add_f32_e32 v124, v121, v124
	v_add_f32_e32 v125, v124, v125
	v_pk_mul_f32 v[120:121], v[8:9], v[8:9]
	v_add_f32_e32 v124, v121, v120
	v_pk_mul_f32 v[120:121], v[10:11], v[10:11]
	v_add_f32_e32 v124, v120, v124
	v_add_f32_e32 v124, v121, v124
	v_add_f32_e32 v125, v124, v125
	v_pk_mul_f32 v[120:121], v[12:13], v[12:13]
	v_add_f32_e32 v124, v121, v120
	v_pk_mul_f32 v[120:121], v[14:15], v[14:15]
	v_add_f32_e32 v124, v120, v124
	v_add_f32_e32 v124, v121, v124
	v_add_f32_e32 v125, v124, v125
	ds_bpermute_b32 v120, v114, v125
	s_waitcnt lgkmcnt(0)
	v_add_f32_e32 v125, v125, v120
	ds_bpermute_b32 v120, v115, v125
	s_waitcnt lgkmcnt(0)
	v_add_f32_e32 v125, v125, v120
	ds_bpermute_b32 v120, v116, v125
	s_waitcnt lgkmcnt(0)
	v_add_f32_e32 v125, v125, v120
	ds_bpermute_b32 v120, v117, v125
	s_waitcnt lgkmcnt(0)
	v_add_f32_e32 v125, v125, v120
	ds_bpermute_b32 v120, v118, v125
	s_waitcnt lgkmcnt(0)
	v_add_f32_e32 v125, v125, v120
	ds_bpermute_b32 v120, v119, v125
	s_waitcnt lgkmcnt(0)
	v_add_f32_e32 v125, v125, v120
	v_fmamk_f32 v125, v125, 0x3a800000, v217
	v_rsq_f32_e32 v122, v125
	s_lshl_b32 s31, s0, 11
	s_add_u32 s6, s62, s31
	s_addc_u32 s7, s63, 0
	v_pk_mul_f32 v[124:125], v[0:1], v[122:123] op_sel_hi:[1,0]
	v_pk_mul_f32 v[124:125], v[64:65], v[124:125]
	v_pk_fma_f32 v[124:125], v[96:97], v[124:125], v[80:81]
	v_pk_mul_f32 v[120:121], v[2:3], v[122:123] op_sel_hi:[1,0]
	v_pk_mul_f32 v[120:121], v[66:67], v[120:121]
	v_pk_fma_f32 v[120:121], v[98:99], v[120:121], v[82:83]
	v_cvt_pk_bf16_f32 v124, v124, v125
	v_cvt_pk_bf16_f32 v125, v120, v121
	global_store_dwordx2 v113, v[124:125], s[6:7] offset:0
	v_pk_mul_f32 v[124:125], v[4:5], v[122:123] op_sel_hi:[1,0]
	v_pk_mul_f32 v[124:125], v[68:69], v[124:125]
	v_pk_fma_f32 v[124:125], v[100:101], v[124:125], v[84:85]
	v_pk_mul_f32 v[120:121], v[6:7], v[122:123] op_sel_hi:[1,0]
	v_pk_mul_f32 v[120:121], v[70:71], v[120:121]
	v_pk_fma_f32 v[120:121], v[102:103], v[120:121], v[86:87]
	v_cvt_pk_bf16_f32 v124, v124, v125
	v_cvt_pk_bf16_f32 v125, v120, v121
	global_store_dwordx2 v113, v[124:125], s[6:7] offset:512
	v_pk_mul_f32 v[124:125], v[8:9], v[122:123] op_sel_hi:[1,0]
	v_pk_mul_f32 v[124:125], v[72:73], v[124:125]
	v_pk_fma_f32 v[124:125], v[104:105], v[124:125], v[88:89]
	v_pk_mul_f32 v[120:121], v[10:11], v[122:123] op_sel_hi:[1,0]
	v_pk_mul_f32 v[120:121], v[74:75], v[120:121]
	v_pk_fma_f32 v[120:121], v[106:107], v[120:121], v[90:91]
	v_cvt_pk_bf16_f32 v124, v124, v125
	v_cvt_pk_bf16_f32 v125, v120, v121
	global_store_dwordx2 v113, v[124:125], s[6:7] offset:1024
	v_pk_mul_f32 v[124:125], v[12:13], v[122:123] op_sel_hi:[1,0]
	v_pk_mul_f32 v[124:125], v[76:77], v[124:125]
	v_pk_fma_f32 v[124:125], v[108:109], v[124:125], v[92:93]
	v_pk_mul_f32 v[120:121], v[14:15], v[122:123] op_sel_hi:[1,0]
	v_pk_mul_f32 v[120:121], v[78:79], v[120:121]
	v_pk_fma_f32 v[120:121], v[110:111], v[120:121], v[94:95]
	v_cvt_pk_bf16_f32 v124, v124, v125
	v_cvt_pk_bf16_f32 v125, v120, v121
	global_store_dwordx2 v113, v[124:125], s[6:7] offset:1536
	s_add_u32 s23, s23, 4
	s_mul_i32 s31, s2, 4
	s_add_i32 s31, s0, s31
	s_cmp_lt_u32 s31, 0x4200
	s_cbranch_scc0 .Lnm_fi0_nopf
	s_cmp_ge_u32 s31, 0x2100
	s_cselect_b32 s6, 1, 0
	s_mul_i32 s7, s6, 0x2100
	s_sub_u32 s7, s31, s7
	s_cmp_ge_u32 s7, 0x2000
	s_cbranch_scc1 .Lnm_fi4_ctxp
	s_lshl_b32 s6, s6, 13
	s_add_u32 s6, s6, s7
	s_lshl_b32 s6, s6, 12
	s_add_u32 s64, s20, s6
	s_addc_u32 s65, s21, 0
	s_branch .Lnm_fi4_ptrd

; __device__ __forceinline__ void norm_phase(KP P, const float* g, const float* MODl, int shc, int scc, bool from_input, int npart) {
;     ...
;         for (int u = 0; u < RU; ++u) { const int row = row0 + u * NGW; ss[u] = 0.f;
;             if (row < M) { const int b = row / RPB, t = row - b * RPB;
;                 const float4* h = from_input ? (t < SEQ ? (const float4*)(P->x + ((size_t)b * SEQ + t) * DM) : (const float4*)(P->ctx + ((size_t)b * CTXL + (t - SEQ)) * DM)) : (const float4*)(H + (size_t)row * DM);
; #pragma unroll
;                 for (int j = 0; j < 4; ++j) { if (from_input) { const f32x4 t4 = __builtin_nontemporal_load((const f32x4*)h + lane + 64 * j); v[u][j] = make_float4(t4[0], t4[1], t4[2], t4[3]); }
;                     else v[u][j] = h[lane + 64 * j]; } } }
.Lnm_fi4_ptrd:
	global_load_dwordx4 v[0:3], v112, s[64:65] offset:0 nt
	global_load_dwordx4 v[4:7], v112, s[64:65] offset:1024 nt
	global_load_dwordx4 v[8:11], v112, s[64:65] offset:2048 nt
	global_load_dwordx4 v[12:15], v112, s[64:65] offset:3072 nt
	s_add_u32 s23, s23, 4
	s_mov_b32 s12, s23

; __device__ __forceinline__ unsigned pk2(float lo, float hi) { return (unsigned)f2bf(lo) | ((unsigned)f2bf(hi) << 16); }
; __device__ __forceinline__ void norm_phase(KP P, const float* g, const float* MODl, int shc, int scc, bool from_input, int npart) {
;     ...
;                 for (int j = 0; j < 4; ++j) ss[u] += v[u][j].x * v[u][j].x + v[u][j].y * v[u][j].y + v[u][j].z * v[u][j].z + v[u][j].w * v[u][j].w;
;                 if (from_input || (t >= SEQ && npart > 0)) {
; #pragma unroll
;                     for (int j = 0; j < 4; ++j) ((float4*)(H + (size_t)row * DM))[lane + 64 * j] = v[u][j]; }
;                 const float r = rsqrtf(wave_sum(ss[u]) * (1.f / DM) + 1e-6f);
;                 const float* sh = MODl + w * NMOD + shc * 1024; const float* sc = MODl + w * NMOD + scc * 1024;
; #pragma unroll
;                 for (int j = 0; j < 4; ++j) { const int c = (lane + 64 * j) * 4; const float4 gg = *(const float4*)(g + c), s4 = *(const float4*)(sh + c), c4 = *(const float4*)(sc + c);
;                     uint2 o; o.x = pk2(v[u][j].x * r * gg.x * (1.f + c4.x) + s4.x, v[u][j].y * r * gg.y * (1.f + c4.y) + s4.y);
;                     o.y = pk2(v[u][j].z * r * gg.z * (1.f + c4.z) + s4.z, v[u][j].w * r * gg.w * (1.f + c4.w) + s4.w);
;                     *(uint2*)(XN + (size_t)row * DM + c) = o; } } }
.Lnm_fi1_tabok:
	global_store_dwordx4 v112, v[16:19], s[64:65] offset:0
	global_store_dwordx4 v112, v[20:23], s[64:65] offset:1024
	global_store_dwordx4 v112, v[24:27], s[64:65] offset:2048
	global_store_dwordx4 v112, v[28:31], s[64:65] offset:3072
	s_add_u32 s23, s23, 4
	v_pk_mul_f32 v[120:121], v[16:17], v[16:17]
	v_add_f32_e32 v125, v121, v120
	v_pk_mul_f32 v[120:121], v[18:19], v[18:19]
	v_add_f32_e32 v125, v120, v125
	v_add_f32_e32 v125, v121, v125
	v_pk_mul_f32 v[120:121], v[20:21], v[20:21]
	v_add_f32_e32 v124, v121, v120
	v_pk_mul_f32 v[120:121], v[22:23], v[22:23]
	v_add_f32_e32 v124, v120, v124
	v_add_f32_e32 v124, v121, v124
	v_add_f32_e32 v125, v124, v125
	v_pk_mul_f32 v[120:121], v[24:25], v[24:25]
	v_add_f32_e32 v124, v121, v120
	v_pk_mul_f32 v[120:121], v[26:27], v[26:27]
	v_add_f32_e32 v124, v120, v124
	v_add_f32_e32 v124, v121, v124
	v_add_f32_e32 v125, v124, v125
	v_pk_mul_f32 v[120:121], v[28:29], v[28:29]
	v_add_f32_e32 v124, v121, v120
	v_pk_mul_f32 v[120:121], v[30:31], v[30:31]
	v_add_f32_e32 v124, v120, v124
	v_add_f32_e32 v124, v121, v124
	v_add_f32_e32 v125, v124, v125
	ds_bpermute_b32 v120, v114, v125
	s_waitcnt lgkmcnt(0)
	v_add_f32_e32 v125, v125, v120
	ds_bpermute_b32 v120, v115, v125
	s_waitcnt lgkmcnt(0)
	v_add_f32_e32 v125, v125, v120
	ds_bpermute_b32 v120, v116, v125
	s_waitcnt lgkmcnt(0)
	v_add_f32_e32 v125, v125, v120
	ds_bpermute_b32 v120, v117, v125
	s_waitcnt lgkmcnt(0)
	v_add_f32_e32 v125, v125, v120
	ds_bpermute_b32 v120, v118, v125
	s_waitcnt lgkmcnt(0)
	v_add_f32_e32 v125, v125, v120
	ds_bpermute_b32 v120, v119, v125
	s_waitcnt lgkmcnt(0)
	v_add_f32_e32 v125, v125, v120
	v_fmamk_f32 v125, v125, 0x3a800000, v217
	v_rsq_f32_e32 v122, v125
	s_lshl_b32 s31, s0, 11
	s_add_u32 s6, s62, s31
	s_addc_u32 s7, s63, 0
	v_pk_mul_f32 v[124:125], v[16:17], v[122:123] op_sel_hi:[1,0]
	v_pk_mul_f32 v[124:125], v[64:65], v[124:125]
	v_pk_fma_f32 v[124:125], v[96:97], v[124:125], v[80:81]
	v_pk_mul_f32 v[120:121], v[18:19], v[122:123] op_sel_hi:[1,0]
	v_pk_mul_f32 v[120:121], v[66:67], v[120:121]
	v_pk_fma_f32 v[120:121], v[98:99], v[120:121], v[82:83]
	v_cvt_pk_bf16_f32 v124, v124, v125
	v_cvt_pk_bf16_f32 v125, v120, v121
	global_store_dwordx2 v113, v[124:125], s[6:7] offset:0
	v_pk_mul_f32 v[124:125], v[20:21], v[122:123] op_sel_hi:[1,0]
	v_pk_mul_f32 v[124:125], v[68:69], v[124:125]
	v_pk_fma_f32 v[124:125], v[100:101], v[124:125], v[84:85]
	v_pk_mul_f32 v[120:121], v[22:23], v[122:123] op_sel_hi:[1,0]
	v_pk_mul_f32 v[120:121], v[70:71], v[120:121]
	v_pk_fma_f32 v[120:121], v[102:103], v[120:121], v[86:87]
	v_cvt_pk_bf16_f32 v124, v124, v125
	v_cvt_pk_bf16_f32 v125, v120, v121
	global_store_dwordx2 v113, v[124:125], s[6:7] offset:512
	v_pk_mul_f32 v[124:125], v[24:25], v[122:123] op_sel_hi:[1,0]
	v_pk_mul_f32 v[124:125], v[72:73], v[124:125]
	v_pk_fma_f32 v[124:125], v[104:105], v[124:125], v[88:89]
	v_pk_mul_f32 v[120:121], v[26:27], v[122:123] op_sel_hi:[1,0]
	v_pk_mul_f32 v[120:121], v[74:75], v[120:121]
	v_pk_fma_f32 v[120:121], v[106:107], v[120:121], v[90:91]
	v_cvt_pk_bf16_f32 v124, v124, v125
	v_cvt_pk_bf16_f32 v125, v120, v121
	global_store_dwordx2 v113, v[124:125], s[6:7] offset:1024
	v_pk_mul_f32 v[124:125], v[28:29], v[122:123] op_sel_hi:[1,0]
	v_pk_mul_f32 v[124:125], v[76:77], v[124:125]
	v_pk_fma_f32 v[124:125], v[108:109], v[124:125], v[92:93]
	v_pk_mul_f32 v[120:121], v[30:31], v[122:123] op_sel_hi:[1,0]
	v_pk_mul_f32 v[120:121], v[78:79], v[120:121]
	v_pk_fma_f32 v[120:121], v[110:111], v[120:121], v[94:95]
	v_cvt_pk_bf16_f32 v124, v124, v125
	v_cvt_pk_bf16_f32 v125, v120, v121
	global_store_dwordx2 v113, v[124:125], s[6:7] offset:1536
	s_add_u32 s23, s23, 4
	s_mul_i32 s31, s2, 4
	s_add_i32 s31, s0, s31
	s_cmp_lt_u32 s31, 0x4200
	s_cbranch_scc0 .Lnm_fi1_nopf
	s_cmp_ge_u32 s31, 0x2100
	s_cselect_b32 s6, 1, 0
	s_mul_i32 s7, s6, 0x2100
	s_sub_u32 s7, s31, s7
	s_cmp_ge_u32 s7, 0x2000
	s_cbranch_scc1 .Lnm_fi5_ctxp
	s_lshl_b32 s6, s6, 13
	s_add_u32 s6, s6, s7
	s_lshl_b32 s6, s6, 12
	s_add_u32 s64, s20, s6
	s_addc_u32 s65, s21, 0
	s_branch .Lnm_fi5_ptrd

; __device__ __forceinline__ void norm_phase(KP P, const float* g, const float* MODl, int shc, int scc, bool from_input, int npart) {
;     ...
;         for (int u = 0; u < RU; ++u) { const int row = row0 + u * NGW; ss[u] = 0.f;
;             if (row < M) { const int b = row / RPB, t = row - b * RPB;
;                 const float4* h = from_input ? (t < SEQ ? (const float4*)(P->x + ((size_t)b * SEQ + t) * DM) : (const float4*)(P->ctx + ((size_t)b * CTXL + (t - SEQ)) * DM)) : (const float4*)(H + (size_t)row * DM);
; #pragma unroll
;                 for (int j = 0; j < 4; ++j) { if (from_input) { const f32x4 t4 = __builtin_nontemporal_load((const f32x4*)h + lane + 64 * j); v[u][j] = make_float4(t4[0], t4[1], t4[2], t4[3]); }
;                     else v[u][j] = h[lane + 64 * j]; } } }
.Lnm_fi5_ptrd:
	global_load_dwordx4 v[16:19], v112, s[64:65] offset:0 nt
	global_load_dwordx4 v[20:23], v112, s[64:65] offset:1024 nt
	global_load_dwordx4 v[24:27], v112, s[64:65] offset:2048 nt
	global_load_dwordx4 v[28:31], v112, s[64:65] offset:3072 nt
	s_add_u32 s23, s23, 4
	s_mov_b32 s13, s23

; __device__ __forceinline__ unsigned pk2(float lo, float hi) { return (unsigned)f2bf(lo) | ((unsigned)f2bf(hi) << 16); }
; __device__ __forceinline__ void norm_phase(KP P, const float* g, const float* MODl, int shc, int scc, bool from_input, int npart) {
;     ...
;                 for (int j = 0; j < 4; ++j) ss[u] += v[u][j].x * v[u][j].x + v[u][j].y * v[u][j].y + v[u][j].z * v[u][j].z + v[u][j].w * v[u][j].w;
;                 if (from_input || (t >= SEQ && npart > 0)) {
; #pragma unroll
;                     for (int j = 0; j < 4; ++j) ((float4*)(H + (size_t)row * DM))[lane + 64 * j] = v[u][j]; }
;                 const float r = rsqrtf(wave_sum(ss[u]) * (1.f / DM) + 1e-6f);
;                 const float* sh = MODl + w * NMOD + shc * 1024; const float* sc = MODl + w * NMOD + scc * 1024;
; #pragma unroll
;                 for (int j = 0; j < 4; ++j) { const int c = (lane + 64 * j) * 4; const float4 gg = *(const float4*)(g + c), s4 = *(const float4*)(sh + c), c4 = *(const float4*)(sc + c);
;                     uint2 o; o.x = pk2(v[u][j].x * r * gg.x * (1.f + c4.x) + s4.x, v[u][j].y * r * gg.y * (1.f + c4.y) + s4.y);
;                     o.y = pk2(v[u][j].z * r * gg.z * (1.f + c4.z) + s4.z, v[u][j].w * r * gg.w * (1.f + c4.w) + s4.w);
;                     *(uint2*)(XN + (size_t)row * DM + c) = o; } } }
.Lnm_fi2_tabok:
	global_store_dwordx4 v112, v[32:35], s[64:65] offset:0
	global_store_dwordx4 v112, v[36:39], s[64:65] offset:1024
	global_store_dwordx4 v112, v[40:43], s[64:65] offset:2048
	global_store_dwordx4 v112, v[44:47], s[64:65] offset:3072
	s_add_u32 s23, s23, 4
	v_pk_mul_f32 v[120:121], v[32:33], v[32:33]
	v_add_f32_e32 v125, v121, v120
	v_pk_mul_f32 v[120:121], v[34:35], v[34:35]
	v_add_f32_e32 v125, v120, v125
	v_add_f32_e32 v125, v121, v125
	v_pk_mul_f32 v[120:121], v[36:37], v[36:37]
	v_add_f32_e32 v124, v121, v120
	v_pk_mul_f32 v[120:121], v[38:39], v[38:39]
	v_add_f32_e32 v124, v120, v124
	v_add_f32_e32 v124, v121, v124
	v_add_f32_e32 v125, v124, v125
	v_pk_mul_f32 v[120:121], v[40:41], v[40:41]
	v_add_f32_e32 v124, v121, v120
	v_pk_mul_f32 v[120:121], v[42:43], v[42:43]
	v_add_f32_e32 v124, v120, v124
	v_add_f32_e32 v124, v121, v124
	v_add_f32_e32 v125, v124, v125
	v_pk_mul_f32 v[120:121], v[44:45], v[44:45]
	v_add_f32_e32 v124, v121, v120
	v_pk_mul_f32 v[120:121], v[46:47], v[46:47]
	v_add_f32_e32 v124, v120, v124
	v_add_f32_e32 v124, v121, v124
	v_add_f32_e32 v125, v124, v125
	ds_bpermute_b32 v120, v114, v125
	s_waitcnt lgkmcnt(0)
	v_add_f32_e32 v125, v125, v120
	ds_bpermute_b32 v120, v115, v125
	s_waitcnt lgkmcnt(0)
	v_add_f32_e32 v125, v125, v120
	ds_bpermute_b32 v120, v116, v125
	s_waitcnt lgkmcnt(0)
	v_add_f32_e32 v125, v125, v120
	ds_bpermute_b32 v120, v117, v125
	s_waitcnt lgkmcnt(0)
	v_add_f32_e32 v125, v125, v120
	ds_bpermute_b32 v120, v118, v125
	s_waitcnt lgkmcnt(0)
	v_add_f32_e32 v125, v125, v120
	ds_bpermute_b32 v120, v119, v125
	s_waitcnt lgkmcnt(0)
	v_add_f32_e32 v125, v125, v120
	v_fmamk_f32 v125, v125, 0x3a800000, v217
	v_rsq_f32_e32 v122, v125
	s_lshl_b32 s31, s0, 11
	s_add_u32 s6, s62, s31
	s_addc_u32 s7, s63, 0
	v_pk_mul_f32 v[124:125], v[32:33], v[122:123] op_sel_hi:[1,0]
	v_pk_mul_f32 v[124:125], v[64:65], v[124:125]
	v_pk_fma_f32 v[124:125], v[96:97], v[124:125], v[80:81]
	v_pk_mul_f32 v[120:121], v[34:35], v[122:123] op_sel_hi:[1,0]
	v_pk_mul_f32 v[120:121], v[66:67], v[120:121]
	v_pk_fma_f32 v[120:121], v[98:99], v[120:121], v[82:83]
	v_cvt_pk_bf16_f32 v124, v124, v125
	v_cvt_pk_bf16_f32 v125, v120, v121
	global_store_dwordx2 v113, v[124:125], s[6:7] offset:0
	v_pk_mul_f32 v[124:125], v[36:37], v[122:123] op_sel_hi:[1,0]
	v_pk_mul_f32 v[124:125], v[68:69], v[124:125]
	v_pk_fma_f32 v[124:125], v[100:101], v[124:125], v[84:85]
	v_pk_mul_f32 v[120:121], v[38:39], v[122:123] op_sel_hi:[1,0]
	v_pk_mul_f32 v[120:121], v[70:71], v[120:121]
	v_pk_fma_f32 v[120:121], v[102:103], v[120:121], v[86:87]
	v_cvt_pk_bf16_f32 v124, v124, v125
	v_cvt_pk_bf16_f32 v125, v120, v121
	global_store_dwordx2 v113, v[124:125], s[6:7] offset:512
	v_pk_mul_f32 v[124:125], v[40:41], v[122:123] op_sel_hi:[1,0]
	v_pk_mul_f32 v[124:125], v[72:73], v[124:125]
	v_pk_fma_f32 v[124:125], v[104:105], v[124:125], v[88:89]
	v_pk_mul_f32 v[120:121], v[42:43], v[122:123] op_sel_hi:[1,0]
	v_pk_mul_f32 v[120:121], v[74:75], v[120:121]
	v_pk_fma_f32 v[120:121], v[106:107], v[120:121], v[90:91]
	v_cvt_pk_bf16_f32 v124, v124, v125
	v_cvt_pk_bf16_f32 v125, v120, v121
	global_store_dwordx2 v113, v[124:125], s[6:7] offset:1024
	v_pk_mul_f32 v[124:125], v[44:45], v[122:123] op_sel_hi:[1,0]
	v_pk_mul_f32 v[124:125], v[76:77], v[124:125]
	v_pk_fma_f32 v[124:125], v[108:109], v[124:125], v[92:93]
	v_pk_mul_f32 v[120:121], v[46:47], v[122:123] op_sel_hi:[1,0]
	v_pk_mul_f32 v[120:121], v[78:79], v[120:121]
	v_pk_fma_f32 v[120:121], v[110:111], v[120:121], v[94:95]
	v_cvt_pk_bf16_f32 v124, v124, v125
	v_cvt_pk_bf16_f32 v125, v120, v121
	global_store_dwordx2 v113, v[124:125], s[6:7] offset:1536
	s_add_u32 s23, s23, 4
	s_mul_i32 s31, s2, 4
	s_add_i32 s31, s0, s31
	s_cmp_lt_u32 s31, 0x4200
	s_cbranch_scc0 .Lnm_fi2_nopf
	s_cmp_ge_u32 s31, 0x2100
	s_cselect_b32 s6, 1, 0
	s_mul_i32 s7, s6, 0x2100
	s_sub_u32 s7, s31, s7
	s_cmp_ge_u32 s7, 0x2000
	s_cbranch_scc1 .Lnm_fi6_ctxp
	s_lshl_b32 s6, s6, 13
	s_add_u32 s6, s6, s7
	s_lshl_b32 s6, s6, 12
	s_add_u32 s64, s20, s6
	s_addc_u32 s65, s21, 0
	s_branch .Lnm_fi6_ptrd

; __device__ __forceinline__ void norm_phase(KP P, const float* g, const float* MODl, int shc, int scc, bool from_input, int npart) {
;     ...
;         for (int u = 0; u < RU; ++u) { const int row = row0 + u * NGW; ss[u] = 0.f;
;             if (row < M) { const int b = row / RPB, t = row - b * RPB;
;                 const float4* h = from_input ? (t < SEQ ? (const float4*)(P->x + ((size_t)b * SEQ + t) * DM) : (const float4*)(P->ctx + ((size_t)b * CTXL + (t - SEQ)) * DM)) : (const float4*)(H + (size_t)row * DM);
; #pragma unroll
;                 for (int j = 0; j < 4; ++j) { if (from_input) { const f32x4 t4 = __builtin_nontemporal_load((const f32x4*)h + lane + 64 * j); v[u][j] = make_float4(t4[0], t4[1], t4[2], t4[3]); }
;                     else v[u][j] = h[lane + 64 * j]; } } }
.Lnm_fi6_ptrd:
	global_load_dwordx4 v[32:35], v112, s[64:65] offset:0 nt
	global_load_dwordx4 v[36:39], v112, s[64:65] offset:1024 nt
	global_load_dwordx4 v[40:43], v112, s[64:65] offset:2048 nt
	global_load_dwordx4 v[44:47], v112, s[64:65] offset:3072 nt
	s_add_u32 s23, s23, 4
	s_mov_b32 s14, s23

; __device__ __forceinline__ unsigned pk2(float lo, float hi) { return (unsigned)f2bf(lo) | ((unsigned)f2bf(hi) << 16); }
; __device__ __forceinline__ void norm_phase(KP P, const float* g, const float* MODl, int shc, int scc, bool from_input, int npart) {
;     ...
;                 for (int j = 0; j < 4; ++j) ss[u] += v[u][j].x * v[u][j].x + v[u][j].y * v[u][j].y + v[u][j].z * v[u][j].z + v[u][j].w * v[u][j].w;
;                 if (from_input || (t >= SEQ && npart > 0)) {
; #pragma unroll
;                     for (int j = 0; j < 4; ++j) ((float4*)(H + (size_t)row * DM))[lane + 64 * j] = v[u][j]; }
;                 const float r = rsqrtf(wave_sum(ss[u]) * (1.f / DM) + 1e-6f);
;                 const float* sh = MODl + w * NMOD + shc * 1024; const float* sc = MODl + w * NMOD + scc * 1024;
; #pragma unroll
;                 for (int j = 0; j < 4; ++j) { const int c = (lane + 64 * j) * 4; const float4 gg = *(const float4*)(g + c), s4 = *(const float4*)(sh + c), c4 = *(const float4*)(sc + c);
;                     uint2 o; o.x = pk2(v[u][j].x * r * gg.x * (1.f + c4.x) + s4.x, v[u][j].y * r * gg.y * (1.f + c4.y) + s4.y);
;                     o.y = pk2(v[u][j].z * r * gg.z * (1.f + c4.z) + s4.z, v[u][j].w * r * gg.w * (1.f + c4.w) + s4.w);
;                     *(uint2*)(XN + (size_t)row * DM + c) = o; } } }
.Lnm_fi3_tabok:
	global_store_dwordx4 v112, v[48:51], s[64:65] offset:0
	global_store_dwordx4 v112, v[52:55], s[64:65] offset:1024
	global_store_dwordx4 v112, v[56:59], s[64:65] offset:2048
	global_store_dwordx4 v112, v[60:63], s[64:65] offset:3072
	s_add_u32 s23, s23, 4
	v_pk_mul_f32 v[120:121], v[48:49], v[48:49]
	v_add_f32_e32 v125, v121, v120
	v_pk_mul_f32 v[120:121], v[50:51], v[50:51]
	v_add_f32_e32 v125, v120, v125
	v_add_f32_e32 v125, v121, v125
	v_pk_mul_f32 v[120:121], v[52:53], v[52:53]
	v_add_f32_e32 v124, v121, v120
	v_pk_mul_f32 v[120:121], v[54:55], v[54:55]
	v_add_f32_e32 v124, v120, v124
	v_add_f32_e32 v124, v121, v124
	v_add_f32_e32 v125, v124, v125
	v_pk_mul_f32 v[120:121], v[56:57], v[56:57]
	v_add_f32_e32 v124, v121, v120
	v_pk_mul_f32 v[120:121], v[58:59], v[58:59]
	v_add_f32_e32 v124, v120, v124
	v_add_f32_e32 v124, v121, v124
	v_add_f32_e32 v125, v124, v125
	v_pk_mul_f32 v[120:121], v[60:61], v[60:61]
	v_add_f32_e32 v124, v121, v120
	v_pk_mul_f32 v[120:121], v[62:63], v[62:63]
	v_add_f32_e32 v124, v120, v124
	v_add_f32_e32 v124, v121, v124
	v_add_f32_e32 v125, v124, v125
	ds_bpermute_b32 v120, v114, v125
	s_waitcnt lgkmcnt(0)
	v_add_f32_e32 v125, v125, v120
	ds_bpermute_b32 v120, v115, v125
	s_waitcnt lgkmcnt(0)
	v_add_f32_e32 v125, v125, v120
	ds_bpermute_b32 v120, v116, v125
	s_waitcnt lgkmcnt(0)
	v_add_f32_e32 v125, v125, v120
	ds_bpermute_b32 v120, v117, v125
	s_waitcnt lgkmcnt(0)
	v_add_f32_e32 v125, v125, v120
	ds_bpermute_b32 v120, v118, v125
	s_waitcnt lgkmcnt(0)
	v_add_f32_e32 v125, v125, v120
	ds_bpermute_b32 v120, v119, v125
	s_waitcnt lgkmcnt(0)
	v_add_f32_e32 v125, v125, v120
	v_fmamk_f32 v125, v125, 0x3a800000, v217
	v_rsq_f32_e32 v122, v125
	s_lshl_b32 s31, s0, 11
	s_add_u32 s6, s62, s31
	s_addc_u32 s7, s63, 0
	v_pk_mul_f32 v[124:125], v[48:49], v[122:123] op_sel_hi:[1,0]
	v_pk_mul_f32 v[124:125], v[64:65], v[124:125]
	v_pk_fma_f32 v[124:125], v[96:97], v[124:125], v[80:81]
	v_pk_mul_f32 v[120:121], v[50:51], v[122:123] op_sel_hi:[1,0]
	v_pk_mul_f32 v[120:121], v[66:67], v[120:121]
	v_pk_fma_f32 v[120:121], v[98:99], v[120:121], v[82:83]
	v_cvt_pk_bf16_f32 v124, v124, v125
	v_cvt_pk_bf16_f32 v125, v120, v121
	global_store_dwordx2 v113, v[124:125], s[6:7] offset:0
	v_pk_mul_f32 v[124:125], v[52:53], v[122:123] op_sel_hi:[1,0]
	v_pk_mul_f32 v[124:125], v[68:69], v[124:125]
	v_pk_fma_f32 v[124:125], v[100:101], v[124:125], v[84:85]
	v_pk_mul_f32 v[120:121], v[54:55], v[122:123] op_sel_hi:[1,0]
	v_pk_mul_f32 v[120:121], v[70:71], v[120:121]
	v_pk_fma_f32 v[120:121], v[102:103], v[120:121], v[86:87]
	v_cvt_pk_bf16_f32 v124, v124, v125
	v_cvt_pk_bf16_f32 v125, v120, v121
	global_store_dwordx2 v113, v[124:125], s[6:7] offset:512
	v_pk_mul_f32 v[124:125], v[56:57], v[122:123] op_sel_hi:[1,0]
	v_pk_mul_f32 v[124:125], v[72:73], v[124:125]
	v_pk_fma_f32 v[124:125], v[104:105], v[124:125], v[88:89]
	v_pk_mul_f32 v[120:121], v[58:59], v[122:123] op_sel_hi:[1,0]
	v_pk_mul_f32 v[120:121], v[74:75], v[120:121]
	v_pk_fma_f32 v[120:121], v[106:107], v[120:121], v[90:91]
	v_cvt_pk_bf16_f32 v124, v124, v125
	v_cvt_pk_bf16_f32 v125, v120, v121
	global_store_dwordx2 v113, v[124:125], s[6:7] offset:1024
	v_pk_mul_f32 v[124:125], v[60:61], v[122:123] op_sel_hi:[1,0]
	v_pk_mul_f32 v[124:125], v[76:77], v[124:125]
	v_pk_fma_f32 v[124:125], v[108:109], v[124:125], v[92:93]
	v_pk_mul_f32 v[120:121], v[62:63], v[122:123] op_sel_hi:[1,0]
	v_pk_mul_f32 v[120:121], v[78:79], v[120:121]
	v_pk_fma_f32 v[120:121], v[110:111], v[120:121], v[94:95]
	v_cvt_pk_bf16_f32 v124, v124, v125
	v_cvt_pk_bf16_f32 v125, v120, v121
	global_store_dwordx2 v113, v[124:125], s[6:7] offset:1536
	s_add_u32 s23, s23, 4
	s_mul_i32 s31, s2, 4
	s_add_i32 s31, s0, s31
	s_cmp_lt_u32 s31, 0x4200
	s_cbranch_scc0 .Lnm_fi3_nopf
	s_cmp_ge_u32 s31, 0x2100
	s_cselect_b32 s6, 1, 0
	s_mul_i32 s7, s6, 0x2100
	s_sub_u32 s7, s31, s7
	s_cmp_ge_u32 s7, 0x2000
	s_cbranch_scc1 .Lnm_fi7_ctxp
	s_lshl_b32 s6, s6, 13
	s_add_u32 s6, s6, s7
	s_lshl_b32 s6, s6, 12
	s_add_u32 s64, s20, s6
	s_addc_u32 s65, s21, 0
	s_branch .Lnm_fi7_ptrd
